# GEMM main loops (proj, w_out, mlp1, mlp2): LDS-DMA loads take the tile base from an SGPR pair (saddr form) instead of a 64-bit VALU add per load; 60 VALU ops per iteration set removed
# speedup vs baseline: 1.0107x; 1.0107x over previous
.LBB0_227:
	s_add_u32 s22, s20, 0xfff80080
	s_addc_u32 s23, s21, -1
	s_add_i32 s59, 0, 0x10000
	v_add_u32_e32 v152, s59, v165
	ds_read_b128 v[140:143], v152
	ds_read_b128 v[144:147], v152 offset:1024
	ds_read_b128 v[148:151], v152 offset:2048
	ds_read_b128 v[170:173], v152 offset:3072
	s_cmp_eq_u32 s58, 28
	s_cselect_b32 s43, s5, s23
	s_cselect_b32 s42, s6, s22
	s_cselect_b32 s23, s7, s57
	s_cselect_b32 s22, s25, s35
	s_add_i32 m0, s49, 0xc000
	ds_read_b128 v[174:177], v168
	ds_read_b128 v[178:181], v168 offset:1024
	ds_read_b128 v[182:185], v168 offset:2048
	ds_read_b128 v[186:189], v168 offset:3072
	ds_read_b128 v[190:193], v168 offset:4096
	ds_read_b128 v[206:209], v168 offset:5120
	ds_read_b128 v[210:213], v168 offset:6144
	ds_read_b128 v[214:217], v168 offset:7168
	global_load_lds_dwordx4 v136, s[20:21]
	s_add_i32 m0, s49, 0xe000
	s_nop 0
	global_load_lds_dwordx4 v138, s[20:21]
	s_waitcnt lgkmcnt(8)
	s_barrier
	s_waitcnt lgkmcnt(0)
	s_setprio 1
	s_waitcnt lgkmcnt(0)
	v_mfma_f32_16x16x32_bf16 v[124:127], v[140:143], v[174:177], v[124:127]
	v_mfma_f32_16x16x32_bf16 v[120:123], v[148:151], v[174:177], v[120:123]
	v_mfma_f32_16x16x32_bf16 v[108:111], v[140:143], v[182:185], v[108:111]
	v_mfma_f32_16x16x32_bf16 v[104:107], v[148:151], v[182:185], v[104:107]
	v_mfma_f32_16x16x32_bf16 v[92:95], v[140:143], v[190:193], v[92:95]
	v_mfma_f32_16x16x32_bf16 v[88:91], v[148:151], v[190:193], v[88:91]
	v_mfma_f32_16x16x32_bf16 v[76:79], v[140:143], v[210:213], v[76:79]
	v_mfma_f32_16x16x32_bf16 v[72:75], v[148:151], v[210:213], v[72:75]
	v_mfma_f32_16x16x32_bf16 v[124:127], v[144:147], v[178:181], v[124:127]
	v_mfma_f32_16x16x32_bf16 v[120:123], v[170:173], v[178:181], v[120:123]
	v_mfma_f32_16x16x32_bf16 v[108:111], v[144:147], v[186:189], v[108:111]
	v_mfma_f32_16x16x32_bf16 v[104:107], v[170:173], v[186:189], v[104:107]
	v_mfma_f32_16x16x32_bf16 v[92:95], v[144:147], v[206:209], v[92:95]
	v_mfma_f32_16x16x32_bf16 v[88:91], v[170:173], v[206:209], v[88:91]
	v_mfma_f32_16x16x32_bf16 v[76:79], v[144:147], v[214:217], v[76:79]
	v_mfma_f32_16x16x32_bf16 v[72:75], v[170:173], v[214:217], v[72:75]
	s_setprio 0
	s_barrier
	s_add_i32 s62, 0, 0x14000
	s_add_i32 s59, s59, s48
	v_add_u32_e32 v152, s62, v165
	s_mov_b32 m0, s59
	ds_read_b128 v[218:221], v152
	ds_read_b128 v[222:225], v152 offset:1024
	ds_read_b128 v[226:229], v152 offset:2048
	ds_read_b128 v[230:233], v152 offset:3072
	global_load_lds_dwordx4 v130, s[22:23]
	s_add_i32 m0, s59, 0x2000
	s_nop 0
	global_load_lds_dwordx4 v134, s[22:23]
	s_barrier
	s_waitcnt lgkmcnt(0)
	s_setprio 1
	s_waitcnt lgkmcnt(0)
	v_mfma_f32_16x16x32_bf16 v[116:119], v[218:221], v[174:177], v[116:119]
	v_mfma_f32_16x16x32_bf16 v[112:115], v[226:229], v[174:177], v[112:115]
	v_mfma_f32_16x16x32_bf16 v[100:103], v[218:221], v[182:185], v[100:103]
	v_mfma_f32_16x16x32_bf16 v[96:99], v[226:229], v[182:185], v[96:99]
	v_mfma_f32_16x16x32_bf16 v[84:87], v[218:221], v[190:193], v[84:87]
	v_mfma_f32_16x16x32_bf16 v[80:83], v[226:229], v[190:193], v[80:83]
	v_mfma_f32_16x16x32_bf16 v[68:71], v[218:221], v[210:213], v[68:71]
	v_mfma_f32_16x16x32_bf16 v[64:67], v[226:229], v[210:213], v[64:67]
	v_mfma_f32_16x16x32_bf16 v[116:119], v[222:225], v[178:181], v[116:119]
	v_mfma_f32_16x16x32_bf16 v[112:115], v[230:233], v[178:181], v[112:115]
	v_mfma_f32_16x16x32_bf16 v[100:103], v[222:225], v[186:189], v[100:103]
	v_mfma_f32_16x16x32_bf16 v[96:99], v[230:233], v[186:189], v[96:99]
	v_mfma_f32_16x16x32_bf16 v[84:87], v[222:225], v[206:209], v[84:87]
	v_mfma_f32_16x16x32_bf16 v[80:83], v[230:233], v[206:209], v[80:83]
	v_mfma_f32_16x16x32_bf16 v[68:71], v[222:225], v[214:217], v[68:71]
	v_mfma_f32_16x16x32_bf16 v[64:67], v[230:233], v[214:217], v[64:67]
	s_setprio 0
	s_mov_b32 m0, s49
	s_add_u32 s98, s42, 0x80
	s_addc_u32 s99, s43, 0
	s_barrier
	ds_read_b128 v[174:177], v168 offset:16384
	ds_read_b128 v[178:181], v168 offset:17408
	ds_read_b128 v[182:185], v168 offset:18432
	ds_read_b128 v[186:189], v168 offset:19456
	ds_read_b128 v[190:193], v168 offset:20480
	ds_read_b128 v[206:209], v168 offset:21504
	ds_read_b128 v[210:213], v168 offset:22528
	ds_read_b128 v[214:217], v168 offset:23552
	global_load_lds_dwordx4 v128, s[42:43]
	s_mov_b32 m0, s50
	s_nop 0
	global_load_lds_dwordx4 v132, s[42:43]
	s_barrier
	s_waitcnt lgkmcnt(0)
	s_setprio 1
	s_waitcnt lgkmcnt(0)
	v_mfma_f32_16x16x32_bf16 v[60:63], v[140:143], v[174:177], v[60:63]
	v_mfma_f32_16x16x32_bf16 v[56:59], v[148:151], v[174:177], v[56:59]
	v_mfma_f32_16x16x32_bf16 v[48:51], v[140:143], v[182:185], v[48:51]
	v_mfma_f32_16x16x32_bf16 v[40:43], v[148:151], v[182:185], v[40:43]
	v_mfma_f32_16x16x32_bf16 v[32:35], v[140:143], v[190:193], v[32:35]
	v_mfma_f32_16x16x32_bf16 v[24:27], v[148:151], v[190:193], v[24:27]
	v_mfma_f32_16x16x32_bf16 v[16:19], v[140:143], v[210:213], v[16:19]
	v_mfma_f32_16x16x32_bf16 v[8:11], v[148:151], v[210:213], v[8:11]
	v_mfma_f32_16x16x32_bf16 v[60:63], v[144:147], v[178:181], v[60:63]
	v_mfma_f32_16x16x32_bf16 v[56:59], v[170:173], v[178:181], v[56:59]
	v_mfma_f32_16x16x32_bf16 v[48:51], v[144:147], v[186:189], v[48:51]
	v_mfma_f32_16x16x32_bf16 v[40:43], v[170:173], v[186:189], v[40:43]
	v_mfma_f32_16x16x32_bf16 v[32:35], v[144:147], v[206:209], v[32:35]
	v_mfma_f32_16x16x32_bf16 v[24:27], v[170:173], v[206:209], v[24:27]
	v_mfma_f32_16x16x32_bf16 v[16:19], v[144:147], v[214:217], v[16:19]
	v_mfma_f32_16x16x32_bf16 v[8:11], v[170:173], v[214:217], v[8:11]
	s_setprio 0
	s_barrier
	s_add_u32 s60, s22, 0x80000
	s_addc_u32 s61, s23, 0
	s_add_i32 s59, s62, s48
	s_mov_b32 m0, s59
	s_nop 0
	global_load_lds_dwordx4 v130, s[60:61]
	s_add_i32 m0, s59, 0x2000
	s_nop 0
	global_load_lds_dwordx4 v134, s[60:61]
	s_waitcnt vmcnt(6)
	s_barrier
	s_setprio 1
	v_mfma_f32_16x16x32_bf16 v[52:55], v[218:221], v[174:177], v[52:55]
	v_mfma_f32_16x16x32_bf16 v[44:47], v[226:229], v[174:177], v[44:47]
	v_mfma_f32_16x16x32_bf16 v[36:39], v[218:221], v[182:185], v[36:39]
	v_mfma_f32_16x16x32_bf16 v[28:31], v[226:229], v[182:185], v[28:31]
	v_mfma_f32_16x16x32_bf16 v[20:23], v[218:221], v[190:193], v[20:23]
	v_mfma_f32_16x16x32_bf16 v[12:15], v[226:229], v[190:193], v[12:15]
	v_mfma_f32_16x16x32_bf16 v[4:7], v[218:221], v[210:213], v[4:7]
	v_mfma_f32_16x16x32_bf16 v[0:3], v[226:229], v[210:213], v[0:3]
	v_mfma_f32_16x16x32_bf16 v[52:55], v[222:225], v[178:181], v[52:55]
	v_mfma_f32_16x16x32_bf16 v[44:47], v[230:233], v[178:181], v[44:47]
	v_mfma_f32_16x16x32_bf16 v[36:39], v[222:225], v[186:189], v[36:39]
	v_mfma_f32_16x16x32_bf16 v[28:31], v[230:233], v[186:189], v[28:31]
	v_mfma_f32_16x16x32_bf16 v[20:23], v[222:225], v[206:209], v[20:23]
	v_mfma_f32_16x16x32_bf16 v[12:15], v[230:233], v[206:209], v[12:15]
	v_mfma_f32_16x16x32_bf16 v[4:7], v[222:225], v[214:217], v[4:7]
	v_mfma_f32_16x16x32_bf16 v[0:3], v[230:233], v[214:217], v[0:3]
	s_setprio 0
	s_add_i32 s59, 0, 0x18000
	v_add_u32_e32 v152, s59, v165
	s_barrier
	ds_read_b128 v[140:143], v152
	ds_read_b128 v[144:147], v152 offset:1024
	ds_read_b128 v[148:151], v152 offset:2048
	ds_read_b128 v[170:173], v152 offset:3072
	s_add_u32 s42, s42, 0x80000
	s_addc_u32 s43, s43, 0
	s_mov_b32 m0, s51
	ds_read_b128 v[174:177], v168 offset:32768
	ds_read_b128 v[178:181], v168 offset:33792
	ds_read_b128 v[182:185], v168 offset:34816
	ds_read_b128 v[186:189], v168 offset:35840
	ds_read_b128 v[190:193], v168 offset:36864
	ds_read_b128 v[206:209], v168 offset:37888
	ds_read_b128 v[210:213], v168 offset:38912
	ds_read_b128 v[214:217], v168 offset:39936
	global_load_lds_dwordx4 v128, s[42:43]
	s_mov_b32 m0, s52
	s_nop 0
	global_load_lds_dwordx4 v132, s[42:43]
	s_waitcnt lgkmcnt(8)
	s_barrier
	s_waitcnt lgkmcnt(0)
	s_setprio 1
	s_waitcnt lgkmcnt(0)
	v_mfma_f32_16x16x32_bf16 v[124:127], v[140:143], v[174:177], v[124:127]
	v_mfma_f32_16x16x32_bf16 v[120:123], v[148:151], v[174:177], v[120:123]
	v_mfma_f32_16x16x32_bf16 v[108:111], v[140:143], v[182:185], v[108:111]
	v_mfma_f32_16x16x32_bf16 v[104:107], v[148:151], v[182:185], v[104:107]
	v_mfma_f32_16x16x32_bf16 v[92:95], v[140:143], v[190:193], v[92:95]
	v_mfma_f32_16x16x32_bf16 v[88:91], v[148:151], v[190:193], v[88:91]
	v_mfma_f32_16x16x32_bf16 v[76:79], v[140:143], v[210:213], v[76:79]
	v_mfma_f32_16x16x32_bf16 v[72:75], v[148:151], v[210:213], v[72:75]
	v_mfma_f32_16x16x32_bf16 v[124:127], v[144:147], v[178:181], v[124:127]
	v_mfma_f32_16x16x32_bf16 v[120:123], v[170:173], v[178:181], v[120:123]
	v_mfma_f32_16x16x32_bf16 v[108:111], v[144:147], v[186:189], v[108:111]
	v_mfma_f32_16x16x32_bf16 v[104:107], v[170:173], v[186:189], v[104:107]
	v_mfma_f32_16x16x32_bf16 v[92:95], v[144:147], v[206:209], v[92:95]
	v_mfma_f32_16x16x32_bf16 v[88:91], v[170:173], v[206:209], v[88:91]
	v_mfma_f32_16x16x32_bf16 v[76:79], v[144:147], v[214:217], v[76:79]
	v_mfma_f32_16x16x32_bf16 v[72:75], v[170:173], v[214:217], v[72:75]
	s_setprio 0
	s_barrier
	s_add_i32 s42, 0, 0x1c000
	s_add_i32 s43, s59, s48
	v_add_u32_e32 v152, s42, v165
	s_add_u32 s100, s22, 0x80
	s_addc_u32 s101, s23, 0
	s_mov_b32 m0, s43
	ds_read_b128 v[218:221], v152
	ds_read_b128 v[222:225], v152 offset:1024
	ds_read_b128 v[226:229], v152 offset:2048
	ds_read_b128 v[230:233], v152 offset:3072
	global_load_lds_dwordx4 v130, s[100:101]
	s_add_i32 m0, s43, 0x2000
	s_nop 0
	global_load_lds_dwordx4 v134, s[100:101]
	s_barrier
	s_waitcnt lgkmcnt(0)
	s_setprio 1
	s_waitcnt lgkmcnt(0)
	v_mfma_f32_16x16x32_bf16 v[116:119], v[218:221], v[174:177], v[116:119]
	v_mfma_f32_16x16x32_bf16 v[112:115], v[226:229], v[174:177], v[112:115]
	v_mfma_f32_16x16x32_bf16 v[100:103], v[218:221], v[182:185], v[100:103]
	v_mfma_f32_16x16x32_bf16 v[96:99], v[226:229], v[182:185], v[96:99]
	v_mfma_f32_16x16x32_bf16 v[84:87], v[218:221], v[190:193], v[84:87]
	v_mfma_f32_16x16x32_bf16 v[80:83], v[226:229], v[190:193], v[80:83]
	v_mfma_f32_16x16x32_bf16 v[68:71], v[218:221], v[210:213], v[68:71]
	v_mfma_f32_16x16x32_bf16 v[64:67], v[226:229], v[210:213], v[64:67]
	v_mfma_f32_16x16x32_bf16 v[116:119], v[222:225], v[178:181], v[116:119]
	v_mfma_f32_16x16x32_bf16 v[112:115], v[230:233], v[178:181], v[112:115]
	v_mfma_f32_16x16x32_bf16 v[100:103], v[222:225], v[186:189], v[100:103]
	v_mfma_f32_16x16x32_bf16 v[96:99], v[230:233], v[186:189], v[96:99]
	v_mfma_f32_16x16x32_bf16 v[84:87], v[222:225], v[206:209], v[84:87]
	v_mfma_f32_16x16x32_bf16 v[80:83], v[230:233], v[206:209], v[80:83]
	v_mfma_f32_16x16x32_bf16 v[68:71], v[222:225], v[214:217], v[68:71]
	v_mfma_f32_16x16x32_bf16 v[64:67], v[230:233], v[214:217], v[64:67]
	s_setprio 0
	s_mov_b32 m0, s53
	s_barrier
	ds_read_b128 v[174:177], v168 offset:49152
	ds_read_b128 v[178:181], v168 offset:50176
	ds_read_b128 v[182:185], v168 offset:51200
	ds_read_b128 v[186:189], v168 offset:52224
	ds_read_b128 v[190:193], v168 offset:53248
	ds_read_b128 v[206:209], v168 offset:54272
	ds_read_b128 v[210:213], v168 offset:55296
	ds_read_b128 v[214:217], v168 offset:56320
	global_load_lds_dwordx4 v128, s[98:99]
	s_mov_b32 m0, s54
	s_nop 0
	global_load_lds_dwordx4 v132, s[98:99]
	s_barrier
	s_waitcnt lgkmcnt(0)
	s_setprio 1
	s_waitcnt lgkmcnt(0)
	v_mfma_f32_16x16x32_bf16 v[60:63], v[140:143], v[174:177], v[60:63]
	v_mfma_f32_16x16x32_bf16 v[56:59], v[148:151], v[174:177], v[56:59]
	v_mfma_f32_16x16x32_bf16 v[48:51], v[140:143], v[182:185], v[48:51]
	v_mfma_f32_16x16x32_bf16 v[40:43], v[148:151], v[182:185], v[40:43]
	v_mfma_f32_16x16x32_bf16 v[32:35], v[140:143], v[190:193], v[32:35]
	v_mfma_f32_16x16x32_bf16 v[24:27], v[148:151], v[190:193], v[24:27]
	v_mfma_f32_16x16x32_bf16 v[16:19], v[140:143], v[210:213], v[16:19]
	v_mfma_f32_16x16x32_bf16 v[8:11], v[148:151], v[210:213], v[8:11]
	v_mfma_f32_16x16x32_bf16 v[60:63], v[144:147], v[178:181], v[60:63]
	v_mfma_f32_16x16x32_bf16 v[56:59], v[170:173], v[178:181], v[56:59]
	v_mfma_f32_16x16x32_bf16 v[48:51], v[144:147], v[186:189], v[48:51]
	v_mfma_f32_16x16x32_bf16 v[40:43], v[170:173], v[186:189], v[40:43]
	v_mfma_f32_16x16x32_bf16 v[32:35], v[144:147], v[206:209], v[32:35]
	v_mfma_f32_16x16x32_bf16 v[24:27], v[170:173], v[206:209], v[24:27]
	v_mfma_f32_16x16x32_bf16 v[16:19], v[144:147], v[214:217], v[16:19]
	v_mfma_f32_16x16x32_bf16 v[8:11], v[170:173], v[214:217], v[8:11]
	s_setprio 0
	s_barrier
	s_add_u32 s22, s22, 0x80080
	s_addc_u32 s23, s23, 0
	s_add_i32 s42, s42, s48
	s_mov_b32 m0, s42
	s_nop 0
	global_load_lds_dwordx4 v130, s[22:23]
	s_add_i32 m0, s42, 0x2000
	s_nop 0
	global_load_lds_dwordx4 v134, s[22:23]
	s_waitcnt vmcnt(6)
	s_barrier
	s_setprio 1
	v_mfma_f32_16x16x32_bf16 v[52:55], v[218:221], v[174:177], v[52:55]
	v_mfma_f32_16x16x32_bf16 v[44:47], v[226:229], v[174:177], v[44:47]
	v_mfma_f32_16x16x32_bf16 v[36:39], v[218:221], v[182:185], v[36:39]
	v_mfma_f32_16x16x32_bf16 v[28:31], v[226:229], v[182:185], v[28:31]
	v_mfma_f32_16x16x32_bf16 v[20:23], v[218:221], v[190:193], v[20:23]
	v_mfma_f32_16x16x32_bf16 v[12:15], v[226:229], v[190:193], v[12:15]
	v_mfma_f32_16x16x32_bf16 v[4:7], v[218:221], v[210:213], v[4:7]
	v_mfma_f32_16x16x32_bf16 v[0:3], v[226:229], v[210:213], v[0:3]
	v_mfma_f32_16x16x32_bf16 v[52:55], v[222:225], v[178:181], v[52:55]
	v_mfma_f32_16x16x32_bf16 v[44:47], v[230:233], v[178:181], v[44:47]
	v_mfma_f32_16x16x32_bf16 v[36:39], v[222:225], v[186:189], v[36:39]
	v_mfma_f32_16x16x32_bf16 v[28:31], v[230:233], v[186:189], v[28:31]
	v_mfma_f32_16x16x32_bf16 v[20:23], v[222:225], v[206:209], v[20:23]
	v_mfma_f32_16x16x32_bf16 v[12:15], v[230:233], v[206:209], v[12:15]
	v_mfma_f32_16x16x32_bf16 v[4:7], v[222:225], v[214:217], v[4:7]
	v_mfma_f32_16x16x32_bf16 v[0:3], v[230:233], v[214:217], v[0:3]
	s_setprio 0
	s_add_i32 s58, s58, 2
	s_add_u32 s20, s20, 0x100
	s_addc_u32 s21, s21, 0
	s_add_u32 s35, s35, 0x100
	s_addc_u32 s57, s57, 0
	s_cmp_gt_u32 s58, 29
	s_barrier
	s_cbranch_scc0 .LBB0_227
	v_lshl_add_u32 v140, s4, 8, v164
	s_cmp_gt_i32 s56, 23
	s_mov_b64 s[20:21], -1
	s_cbranch_scc1 .LBB0_262
	s_cmp_lt_i32 s56, 4
	s_cselect_b64 s[4:5], -1, 0
	s_and_b32 s6, s56, 0x7ffffffc
	s_cmp_eq_u32 s6, 16
	s_cselect_b64 s[6:7], -1, 0
	s_or_b64 s[20:21], s[4:5], s[6:7]
	s_and_b64 vcc, exec, s[20:21]
	v_mov_b32_e32 v149, v123
	v_mov_b32_e32 v148, v122
	v_mov_b32_e32 v163, v121
	v_mov_b32_e32 v162, v120
	v_mov_b32_e32 v147, v127
	v_mov_b32_e32 v146, v126
	v_mov_b32_e32 v151, v125
	v_mov_b32_e32 v150, v124
	s_cbranch_vccz .LBB0_231
	v_mul_f32_e32 v141, 0xbfb8aa3b, v124
	v_exp_f32_e32 v141, v141
	v_mul_f32_e32 v142, 0xbfb8aa3b, v120
	v_mul_f32_e32 v145, 0xbfb8aa3b, v126
	v_mul_f32_e32 v143, 0xbfb8aa3b, v125
	v_exp_f32_e32 v144, v142
	v_exp_f32_e32 v145, v145
	v_mul_f32_e32 v146, 0xbfb8aa3b, v122
	v_exp_f32_e32 v143, v143
	v_exp_f32_e32 v147, v146
	v_add_f32_e32 v141, 1.0, v141
	v_rcp_f32_e32 v142, v141
	v_add_f32_e32 v141, 1.0, v144
	v_add_f32_e32 v145, 1.0, v145
	v_rcp_f32_e32 v144, v141
	v_add_f32_e32 v141, 1.0, v143
	v_rcp_f32_e32 v146, v145
	v_add_f32_e32 v145, 1.0, v147
	v_mul_f32_e32 v147, 0xbfb8aa3b, v127
	v_rcp_f32_e32 v143, v141
	v_mul_f32_e32 v141, 0xbfb8aa3b, v121
	v_exp_f32_e32 v147, v147
	v_mul_f32_e32 v148, 0xbfb8aa3b, v123
	v_exp_f32_e32 v141, v141
	v_exp_f32_e32 v149, v148
	v_rcp_f32_e32 v148, v145
	v_add_f32_e32 v145, 1.0, v147
	v_add_f32_e32 v141, 1.0, v141
	v_rcp_f32_e32 v147, v145
	v_add_f32_e32 v145, 1.0, v149
	v_rcp_f32_e32 v149, v145
	v_rcp_f32_e32 v145, v141
	v_pk_mul_f32 v[146:147], v[126:127], v[146:147]
	v_pk_mul_f32 v[150:151], v[124:125], v[142:143]
	v_pk_mul_f32 v[148:149], v[122:123], v[148:149]
	v_pk_mul_f32 v[162:163], v[120:121], v[144:145]

.LBB0_561:
	s_add_u32 s38, s22, 0xfff80080
	s_addc_u32 s39, s23, -1
	s_add_i32 s84, 0, 0x10000
	v_add_u32_e32 v92, s84, v206
	ds_read_b128 v[72:75], v92
	ds_read_b128 v[76:79], v92 offset:1024
	ds_read_b128 v[84:87], v92 offset:2048
	ds_read_b128 v[92:95], v92 offset:3072
	s_cmp_eq_u32 s30, 28
	s_cselect_b32 s53, s5, s39
	s_cselect_b32 s52, s6, s38
	s_cselect_b32 s39, s1, s21
	s_cselect_b32 s38, s7, s17
	s_add_i32 m0, s61, 0xc000
	ds_read_b128 v[144:147], v208
	ds_read_b128 v[148:151], v208 offset:1024
	ds_read_b128 v[188:191], v208 offset:2048
	ds_read_b128 v[210:213], v208 offset:3072
	ds_read_b128 v[214:217], v208 offset:4096
	ds_read_b128 v[218:221], v208 offset:5120
	ds_read_b128 v[222:225], v208 offset:6144
	ds_read_b128 v[226:229], v208 offset:7168
	global_load_lds_dwordx4 v184, s[22:23]
	s_add_i32 m0, s61, 0xe000
	s_nop 0
	global_load_lds_dwordx4 v186, s[22:23]
	s_waitcnt lgkmcnt(8)
	s_barrier
	s_waitcnt lgkmcnt(0)
	s_setprio 1
	s_waitcnt lgkmcnt(0)
	v_mfma_f32_16x16x32_bf16 v[140:143], v[72:75], v[144:147], v[140:143]
	v_mfma_f32_16x16x32_bf16 v[136:139], v[84:87], v[144:147], v[136:139]
	v_mfma_f32_16x16x32_bf16 v[124:127], v[72:75], v[188:191], v[124:127]
	v_mfma_f32_16x16x32_bf16 v[120:123], v[84:87], v[188:191], v[120:123]
	v_mfma_f32_16x16x32_bf16 v[108:111], v[72:75], v[214:217], v[108:111]
	v_mfma_f32_16x16x32_bf16 v[104:107], v[84:87], v[214:217], v[104:107]
	v_mfma_f32_16x16x32_bf16 v[88:91], v[72:75], v[222:225], v[88:91]
	v_mfma_f32_16x16x32_bf16 v[80:83], v[84:87], v[222:225], v[80:83]
	v_mfma_f32_16x16x32_bf16 v[140:143], v[76:79], v[148:151], v[140:143]
	v_mfma_f32_16x16x32_bf16 v[136:139], v[92:95], v[148:151], v[136:139]
	v_mfma_f32_16x16x32_bf16 v[124:127], v[76:79], v[210:213], v[124:127]
	v_mfma_f32_16x16x32_bf16 v[120:123], v[92:95], v[210:213], v[120:123]
	v_mfma_f32_16x16x32_bf16 v[108:111], v[76:79], v[218:221], v[108:111]
	v_mfma_f32_16x16x32_bf16 v[104:107], v[92:95], v[218:221], v[104:107]
	v_mfma_f32_16x16x32_bf16 v[88:91], v[76:79], v[226:229], v[88:91]
	v_mfma_f32_16x16x32_bf16 v[80:83], v[92:95], v[226:229], v[80:83]
	s_setprio 0
	s_barrier
	s_add_i32 s86, 0, 0x14000
	v_add_u32_e32 v192, s86, v206
	s_add_i32 s84, s84, s60
	ds_read_b128 v[230:233], v192
	ds_read_b128 v[234:237], v192 offset:1024
	ds_read_b128 v[238:241], v192 offset:2048
	ds_read_b128 v[242:245], v192 offset:3072
	s_mov_b32 m0, s84
	s_nop 0
	global_load_lds_dwordx4 v152, s[38:39]
	s_add_i32 m0, s84, 0x2000
	s_nop 0
	global_load_lds_dwordx4 v162, s[38:39]
	s_barrier
	s_waitcnt lgkmcnt(0)
	s_setprio 1
	s_waitcnt lgkmcnt(0)
	v_mfma_f32_16x16x32_bf16 v[132:135], v[230:233], v[144:147], v[132:135]
	v_mfma_f32_16x16x32_bf16 v[128:131], v[238:241], v[144:147], v[128:131]
	v_mfma_f32_16x16x32_bf16 v[116:119], v[230:233], v[188:191], v[116:119]
	v_mfma_f32_16x16x32_bf16 v[112:115], v[238:241], v[188:191], v[112:115]
	v_mfma_f32_16x16x32_bf16 v[100:103], v[230:233], v[214:217], v[100:103]
	v_mfma_f32_16x16x32_bf16 v[96:99], v[238:241], v[214:217], v[96:99]
	v_mfma_f32_16x16x32_bf16 v[68:71], v[230:233], v[222:225], v[68:71]
	v_mfma_f32_16x16x32_bf16 v[64:67], v[238:241], v[222:225], v[64:67]
	v_mfma_f32_16x16x32_bf16 v[132:135], v[234:237], v[148:151], v[132:135]
	v_mfma_f32_16x16x32_bf16 v[128:131], v[242:245], v[148:151], v[128:131]
	v_mfma_f32_16x16x32_bf16 v[116:119], v[234:237], v[210:213], v[116:119]
	v_mfma_f32_16x16x32_bf16 v[112:115], v[242:245], v[210:213], v[112:115]
	v_mfma_f32_16x16x32_bf16 v[100:103], v[234:237], v[218:221], v[100:103]
	v_mfma_f32_16x16x32_bf16 v[96:99], v[242:245], v[218:221], v[96:99]
	v_mfma_f32_16x16x32_bf16 v[68:71], v[234:237], v[226:229], v[68:71]
	v_mfma_f32_16x16x32_bf16 v[64:67], v[242:245], v[226:229], v[64:67]
	s_setprio 0
	s_mov_b32 m0, s61
	s_add_u32 s98, s52, 0x80
	s_addc_u32 s99, s53, 0
	s_barrier
	ds_read_b128 v[144:147], v208 offset:16384
	ds_read_b128 v[148:151], v208 offset:17408
	ds_read_b128 v[188:191], v208 offset:18432
	ds_read_b128 v[210:213], v208 offset:19456
	ds_read_b128 v[214:217], v208 offset:20480
	ds_read_b128 v[218:221], v208 offset:21504
	ds_read_b128 v[222:225], v208 offset:22528
	ds_read_b128 v[226:229], v208 offset:23552
	global_load_lds_dwordx4 v166, s[52:53]
	s_mov_b32 m0, s62
	s_nop 0
	global_load_lds_dwordx4 v164, s[52:53]
	s_barrier
	s_waitcnt lgkmcnt(0)
	s_setprio 1
	s_waitcnt lgkmcnt(0)
	v_mfma_f32_16x16x32_bf16 v[60:63], v[72:75], v[144:147], v[60:63]
	v_mfma_f32_16x16x32_bf16 v[56:59], v[84:87], v[144:147], v[56:59]
	v_mfma_f32_16x16x32_bf16 v[44:47], v[72:75], v[188:191], v[44:47]
	v_mfma_f32_16x16x32_bf16 v[40:43], v[84:87], v[188:191], v[40:43]
	v_mfma_f32_16x16x32_bf16 v[28:31], v[72:75], v[214:217], v[28:31]
	v_mfma_f32_16x16x32_bf16 v[24:27], v[84:87], v[214:217], v[24:27]
	v_mfma_f32_16x16x32_bf16 v[12:15], v[72:75], v[222:225], v[12:15]
	v_mfma_f32_16x16x32_bf16 v[8:11], v[84:87], v[222:225], v[8:11]
	v_mfma_f32_16x16x32_bf16 v[60:63], v[76:79], v[148:151], v[60:63]
	v_mfma_f32_16x16x32_bf16 v[56:59], v[92:95], v[148:151], v[56:59]
	v_mfma_f32_16x16x32_bf16 v[44:47], v[76:79], v[210:213], v[44:47]
	v_mfma_f32_16x16x32_bf16 v[40:43], v[92:95], v[210:213], v[40:43]
	v_mfma_f32_16x16x32_bf16 v[28:31], v[76:79], v[218:221], v[28:31]
	v_mfma_f32_16x16x32_bf16 v[24:27], v[92:95], v[218:221], v[24:27]
	v_mfma_f32_16x16x32_bf16 v[12:15], v[76:79], v[226:229], v[12:15]
	v_mfma_f32_16x16x32_bf16 v[8:11], v[92:95], v[226:229], v[8:11]
	s_setprio 0
	s_barrier
	s_add_u32 s84, s38, 0x80000
	s_addc_u32 s85, s39, 0
	s_add_i32 s86, s86, s60
	s_mov_b32 m0, s86
	s_nop 0
	global_load_lds_dwordx4 v152, s[84:85]
	s_add_i32 m0, s86, 0x2000
	s_nop 0
	global_load_lds_dwordx4 v162, s[84:85]
	s_waitcnt vmcnt(6)
	s_barrier
	s_setprio 1
	v_mfma_f32_16x16x32_bf16 v[52:55], v[230:233], v[144:147], v[52:55]
	v_mfma_f32_16x16x32_bf16 v[48:51], v[238:241], v[144:147], v[48:51]
	v_mfma_f32_16x16x32_bf16 v[36:39], v[230:233], v[188:191], v[36:39]
	v_mfma_f32_16x16x32_bf16 v[32:35], v[238:241], v[188:191], v[32:35]
	v_mfma_f32_16x16x32_bf16 v[20:23], v[230:233], v[214:217], v[20:23]
	v_mfma_f32_16x16x32_bf16 v[16:19], v[238:241], v[214:217], v[16:19]
	v_mfma_f32_16x16x32_bf16 v[4:7], v[230:233], v[222:225], v[4:7]
	v_mfma_f32_16x16x32_bf16 v[0:3], v[238:241], v[222:225], v[0:3]
	v_mfma_f32_16x16x32_bf16 v[52:55], v[234:237], v[148:151], v[52:55]
	v_mfma_f32_16x16x32_bf16 v[48:51], v[242:245], v[148:151], v[48:51]
	v_mfma_f32_16x16x32_bf16 v[36:39], v[234:237], v[210:213], v[36:39]
	v_mfma_f32_16x16x32_bf16 v[32:35], v[242:245], v[210:213], v[32:35]
	v_mfma_f32_16x16x32_bf16 v[20:23], v[234:237], v[218:221], v[20:23]
	v_mfma_f32_16x16x32_bf16 v[16:19], v[242:245], v[218:221], v[16:19]
	v_mfma_f32_16x16x32_bf16 v[4:7], v[234:237], v[226:229], v[4:7]
	v_mfma_f32_16x16x32_bf16 v[0:3], v[242:245], v[226:229], v[0:3]
	s_setprio 0
	s_add_i32 s84, 0, 0x18000
	v_add_u32_e32 v92, s84, v206
	s_barrier
	ds_read_b128 v[72:75], v92
	ds_read_b128 v[76:79], v92 offset:1024
	ds_read_b128 v[84:87], v92 offset:2048
	ds_read_b128 v[92:95], v92 offset:3072
	s_add_u32 s52, s52, 0x80000
	s_addc_u32 s53, s53, 0
	s_mov_b32 m0, s63
	ds_read_b128 v[144:147], v208 offset:32768
	ds_read_b128 v[148:151], v208 offset:33792
	ds_read_b128 v[188:191], v208 offset:34816
	ds_read_b128 v[210:213], v208 offset:35840
	ds_read_b128 v[214:217], v208 offset:36864
	ds_read_b128 v[218:221], v208 offset:37888
	ds_read_b128 v[222:225], v208 offset:38912
	ds_read_b128 v[226:229], v208 offset:39936
	global_load_lds_dwordx4 v166, s[52:53]
	s_mov_b32 m0, s68
	s_nop 0
	global_load_lds_dwordx4 v164, s[52:53]
	s_waitcnt lgkmcnt(8)
	s_barrier
	s_waitcnt lgkmcnt(0)
	s_setprio 1
	s_waitcnt lgkmcnt(0)
	v_mfma_f32_16x16x32_bf16 v[140:143], v[72:75], v[144:147], v[140:143]
	v_mfma_f32_16x16x32_bf16 v[136:139], v[84:87], v[144:147], v[136:139]
	v_mfma_f32_16x16x32_bf16 v[124:127], v[72:75], v[188:191], v[124:127]
	v_mfma_f32_16x16x32_bf16 v[120:123], v[84:87], v[188:191], v[120:123]
	v_mfma_f32_16x16x32_bf16 v[108:111], v[72:75], v[214:217], v[108:111]
	v_mfma_f32_16x16x32_bf16 v[104:107], v[84:87], v[214:217], v[104:107]
	v_mfma_f32_16x16x32_bf16 v[88:91], v[72:75], v[222:225], v[88:91]
	v_mfma_f32_16x16x32_bf16 v[80:83], v[84:87], v[222:225], v[80:83]
	v_mfma_f32_16x16x32_bf16 v[140:143], v[76:79], v[148:151], v[140:143]
	v_mfma_f32_16x16x32_bf16 v[136:139], v[92:95], v[148:151], v[136:139]
	v_mfma_f32_16x16x32_bf16 v[124:127], v[76:79], v[210:213], v[124:127]
	v_mfma_f32_16x16x32_bf16 v[120:123], v[92:95], v[210:213], v[120:123]
	v_mfma_f32_16x16x32_bf16 v[108:111], v[76:79], v[218:221], v[108:111]
	v_mfma_f32_16x16x32_bf16 v[104:107], v[92:95], v[218:221], v[104:107]
	v_mfma_f32_16x16x32_bf16 v[88:91], v[76:79], v[226:229], v[88:91]
	v_mfma_f32_16x16x32_bf16 v[80:83], v[92:95], v[226:229], v[80:83]
	s_setprio 0
	s_barrier
	s_add_i32 s52, 0, 0x1c000
	s_add_i32 s53, s84, s60
	v_add_u32_e32 v209, s52, v206
	s_add_u32 s100, s38, 0x80
	s_addc_u32 s101, s39, 0
	s_mov_b32 m0, s53
	ds_read_b128 v[230:233], v209
	ds_read_b128 v[234:237], v209 offset:1024
	ds_read_b128 v[238:241], v209 offset:2048
	ds_read_b128 v[242:245], v209 offset:3072
	global_load_lds_dwordx4 v152, s[100:101]
	s_add_i32 m0, s53, 0x2000
	s_nop 0
	global_load_lds_dwordx4 v162, s[100:101]
	s_barrier
	s_waitcnt lgkmcnt(0)
	s_setprio 1
	s_waitcnt lgkmcnt(0)
	v_mfma_f32_16x16x32_bf16 v[132:135], v[230:233], v[144:147], v[132:135]
	v_mfma_f32_16x16x32_bf16 v[128:131], v[238:241], v[144:147], v[128:131]
	v_mfma_f32_16x16x32_bf16 v[116:119], v[230:233], v[188:191], v[116:119]
	v_mfma_f32_16x16x32_bf16 v[112:115], v[238:241], v[188:191], v[112:115]
	v_mfma_f32_16x16x32_bf16 v[100:103], v[230:233], v[214:217], v[100:103]
	v_mfma_f32_16x16x32_bf16 v[96:99], v[238:241], v[214:217], v[96:99]
	v_mfma_f32_16x16x32_bf16 v[68:71], v[230:233], v[222:225], v[68:71]
	v_mfma_f32_16x16x32_bf16 v[64:67], v[238:241], v[222:225], v[64:67]
	v_mfma_f32_16x16x32_bf16 v[132:135], v[234:237], v[148:151], v[132:135]
	v_mfma_f32_16x16x32_bf16 v[128:131], v[242:245], v[148:151], v[128:131]
	v_mfma_f32_16x16x32_bf16 v[116:119], v[234:237], v[210:213], v[116:119]
	v_mfma_f32_16x16x32_bf16 v[112:115], v[242:245], v[210:213], v[112:115]
	v_mfma_f32_16x16x32_bf16 v[100:103], v[234:237], v[218:221], v[100:103]
	v_mfma_f32_16x16x32_bf16 v[96:99], v[242:245], v[218:221], v[96:99]
	v_mfma_f32_16x16x32_bf16 v[68:71], v[234:237], v[226:229], v[68:71]
	v_mfma_f32_16x16x32_bf16 v[64:67], v[242:245], v[226:229], v[64:67]
	s_setprio 0
	s_mov_b32 m0, s81
	s_barrier
	ds_read_b128 v[144:147], v208 offset:49152
	ds_read_b128 v[148:151], v208 offset:50176
	ds_read_b128 v[188:191], v208 offset:51200
	ds_read_b128 v[210:213], v208 offset:52224
	ds_read_b128 v[214:217], v208 offset:53248
	ds_read_b128 v[218:221], v208 offset:54272
	ds_read_b128 v[222:225], v208 offset:55296
	ds_read_b128 v[226:229], v208 offset:56320
	global_load_lds_dwordx4 v166, s[98:99]
	s_mov_b32 m0, s82
	s_nop 0
	global_load_lds_dwordx4 v164, s[98:99]
	s_barrier
	s_waitcnt lgkmcnt(0)
	s_setprio 1
	s_waitcnt lgkmcnt(0)
	v_mfma_f32_16x16x32_bf16 v[60:63], v[72:75], v[144:147], v[60:63]
	v_mfma_f32_16x16x32_bf16 v[56:59], v[84:87], v[144:147], v[56:59]
	v_mfma_f32_16x16x32_bf16 v[44:47], v[72:75], v[188:191], v[44:47]
	v_mfma_f32_16x16x32_bf16 v[40:43], v[84:87], v[188:191], v[40:43]
	v_mfma_f32_16x16x32_bf16 v[28:31], v[72:75], v[214:217], v[28:31]
	v_mfma_f32_16x16x32_bf16 v[24:27], v[84:87], v[214:217], v[24:27]
	v_mfma_f32_16x16x32_bf16 v[12:15], v[72:75], v[222:225], v[12:15]
	v_mfma_f32_16x16x32_bf16 v[8:11], v[84:87], v[222:225], v[8:11]
	v_mfma_f32_16x16x32_bf16 v[60:63], v[76:79], v[148:151], v[60:63]
	v_mfma_f32_16x16x32_bf16 v[56:59], v[92:95], v[148:151], v[56:59]
	v_mfma_f32_16x16x32_bf16 v[44:47], v[76:79], v[210:213], v[44:47]
	v_mfma_f32_16x16x32_bf16 v[40:43], v[92:95], v[210:213], v[40:43]
	v_mfma_f32_16x16x32_bf16 v[28:31], v[76:79], v[218:221], v[28:31]
	v_mfma_f32_16x16x32_bf16 v[24:27], v[92:95], v[218:221], v[24:27]
	v_mfma_f32_16x16x32_bf16 v[12:15], v[76:79], v[226:229], v[12:15]
	v_mfma_f32_16x16x32_bf16 v[8:11], v[92:95], v[226:229], v[8:11]
	s_setprio 0
	s_barrier
	s_add_u32 s38, s38, 0x80080
	s_addc_u32 s39, s39, 0
	s_add_i32 s52, s52, s60
	s_mov_b32 m0, s52
	s_nop 0
	global_load_lds_dwordx4 v152, s[38:39]
	s_add_i32 m0, s52, 0x2000
	s_nop 0
	global_load_lds_dwordx4 v162, s[38:39]
	s_waitcnt vmcnt(6)
	s_barrier
	s_setprio 1
	v_mfma_f32_16x16x32_bf16 v[52:55], v[230:233], v[144:147], v[52:55]
	v_mfma_f32_16x16x32_bf16 v[48:51], v[238:241], v[144:147], v[48:51]
	v_mfma_f32_16x16x32_bf16 v[36:39], v[230:233], v[188:191], v[36:39]
	v_mfma_f32_16x16x32_bf16 v[32:35], v[238:241], v[188:191], v[32:35]
	v_mfma_f32_16x16x32_bf16 v[20:23], v[230:233], v[214:217], v[20:23]
	v_mfma_f32_16x16x32_bf16 v[16:19], v[238:241], v[214:217], v[16:19]
	v_mfma_f32_16x16x32_bf16 v[4:7], v[230:233], v[222:225], v[4:7]
	v_mfma_f32_16x16x32_bf16 v[0:3], v[238:241], v[222:225], v[0:3]
	v_mfma_f32_16x16x32_bf16 v[52:55], v[234:237], v[148:151], v[52:55]
	v_mfma_f32_16x16x32_bf16 v[48:51], v[242:245], v[148:151], v[48:51]
	v_mfma_f32_16x16x32_bf16 v[36:39], v[234:237], v[210:213], v[36:39]
	v_mfma_f32_16x16x32_bf16 v[32:35], v[242:245], v[210:213], v[32:35]
	v_mfma_f32_16x16x32_bf16 v[20:23], v[234:237], v[218:221], v[20:23]
	v_mfma_f32_16x16x32_bf16 v[16:19], v[242:245], v[218:221], v[16:19]
	v_mfma_f32_16x16x32_bf16 v[4:7], v[234:237], v[226:229], v[4:7]
	v_mfma_f32_16x16x32_bf16 v[0:3], v[242:245], v[226:229], v[0:3]
	s_setprio 0
	s_add_i32 s30, s30, 2
	s_add_u32 s22, s22, 0x100
	s_addc_u32 s23, s23, 0
	s_add_u32 s17, s17, 0x100
	s_addc_u32 s21, s21, 0
	s_cmp_gt_u32 s30, 29
	s_barrier
	s_cbranch_scc0 .LBB0_561
	v_lshl_or_b32 v188, s4, 8, v207
	v_ashrrev_i32_e32 v189, 31, v188
	s_cmp_lt_i32 s20, 16
	s_cselect_b32 s6, s44, s46
	s_cselect_b32 s7, s45, s47
	s_cselect_b32 s1, 0, 16
	s_sub_i32 s4, s20, s1
	s_mov_b32 s5, 0
	s_lshl_b64 s[4:5], s[4:5], 21
	s_add_u32 s38, s6, s4
	s_addc_u32 s39, s7, s5
	s_cmp_lt_i32 s20, 32
	s_cselect_b32 s1, 0x3000, s73
	s_cmp_lt_i32 s20, 16
	s_cselect_b32 s1, 0, s1
	s_lshl_b32 s1, s1, 2
	s_add_u32 s6, s79, s1
	s_addc_u32 s7, s80, 0
	s_mov_b32 s4, s20
	s_mov_b32 s5, 0
	s_lshl_b64 s[4:5], s[4:5], 20
	s_add_u32 s52, s69, s4
	s_addc_u32 s53, s78, s5
	v_lshl_add_u64 v[190:191], v[188:189], 2, s[6:7]
	s_mov_b64 s[4:5], 0x28504000
	v_lshl_add_u64 v[190:191], v[190:191], 0, s[4:5]
	global_load_dwordx4 v[92:95], v[190:191], off
	global_load_dwordx4 v[84:87], v[190:191], off offset:16
	global_load_dwordx4 v[76:79], v[190:191], off offset:512
	global_load_dwordx4 v[72:75], v[190:191], off offset:528
	v_lshl_add_u64 v[144:145], v[188:189], 1, s[52:53]
	s_and_b64 vcc, exec, s[64:65]
	s_cbranch_vccz .Lwo_epi_f32
	v_lshl_add_u64 v[148:149], v[168:169], 1, v[144:145]
	global_load_dwordx4 v[210:213], v[148:149], off
	global_load_dwordx4 v[214:217], v[148:149], off offset:256
	v_lshl_add_u64 v[148:149], v[170:171], 1, v[144:145]
	global_load_dwordx4 v[218:221], v[148:149], off
	global_load_dwordx4 v[222:225], v[148:149], off offset:256
	v_lshl_add_u64 v[148:149], v[172:173], 1, v[144:145]
	global_load_dwordx4 v[226:229], v[148:149], off
	global_load_dwordx4 v[230:233], v[148:149], off offset:256
	v_lshl_add_u64 v[148:149], v[174:175], 1, v[144:145]
	global_load_dwordx4 v[234:237], v[148:149], off
	global_load_dwordx4 v[238:241], v[148:149], off offset:256
	v_lshl_add_u64 v[148:149], v[176:177], 1, v[144:145]
	global_load_dwordx4 v[242:245], v[148:149], off
	s_waitcnt vmcnt(8)
	v_lshlrev_b32_e32 v188, 16, v210
	v_and_b32_e32 v189, 0xffff0000, v210
	v_lshlrev_b32_e32 v190, 16, v211
	v_and_b32_e32 v191, 0xffff0000, v211
	v_lshlrev_b32_e32 v246, 16, v212
	v_and_b32_e32 v247, 0xffff0000, v212
	v_lshlrev_b32_e32 v248, 16, v213
	v_and_b32_e32 v249, 0xffff0000, v213
	global_load_dwordx4 v[210:213], v[148:149], off offset:256
	v_lshl_add_u64 v[150:151], v[168:169], 1, v[144:145]
	v_pk_fma_f32 v[140:141], v[140:141], v[92:93], v[188:189]
	v_pk_fma_f32 v[142:143], v[142:143], v[94:95], v[190:191]
	v_pk_fma_f32 v[136:137], v[136:137], v[84:85], v[246:247]
	v_pk_fma_f32 v[138:139], v[138:139], v[86:87], v[248:249]
	v_cvt_pk_bf16_f32 v140, v140, v141
	v_cvt_pk_bf16_f32 v141, v142, v143
	v_cvt_pk_bf16_f32 v142, v136, v137
	v_cvt_pk_bf16_f32 v143, v138, v139
	global_store_dwordx4 v[150:151], v[140:143], off
	s_waitcnt vmcnt(9)
	v_lshlrev_b32_e32 v188, 16, v214
	v_and_b32_e32 v189, 0xffff0000, v214
	v_lshlrev_b32_e32 v190, 16, v215
	v_and_b32_e32 v191, 0xffff0000, v215
	v_lshlrev_b32_e32 v246, 16, v216
	v_and_b32_e32 v247, 0xffff0000, v216
	v_lshlrev_b32_e32 v248, 16, v217
	v_and_b32_e32 v249, 0xffff0000, v217
	v_lshl_add_u64 v[148:149], v[178:179], 1, v[144:145]
	global_load_dwordx4 v[214:217], v[148:149], off
	v_pk_fma_f32 v[132:133], v[132:133], v[76:77], v[188:189]
	v_pk_fma_f32 v[134:135], v[134:135], v[78:79], v[190:191]
	v_pk_fma_f32 v[128:129], v[128:129], v[72:73], v[246:247]
	v_pk_fma_f32 v[130:131], v[130:131], v[74:75], v[248:249]
	v_cvt_pk_bf16_f32 v132, v132, v133
	v_cvt_pk_bf16_f32 v133, v134, v135
	v_cvt_pk_bf16_f32 v134, v128, v129
	v_cvt_pk_bf16_f32 v135, v130, v131
	global_store_dwordx4 v[150:151], v[132:135], off offset:256
	s_waitcnt vmcnt(10)
	v_lshlrev_b32_e32 v188, 16, v218
	v_and_b32_e32 v189, 0xffff0000, v218
	v_lshlrev_b32_e32 v190, 16, v219
	v_and_b32_e32 v191, 0xffff0000, v219
	v_lshlrev_b32_e32 v246, 16, v220
	v_and_b32_e32 v247, 0xffff0000, v220
	v_lshlrev_b32_e32 v248, 16, v221
	v_and_b32_e32 v249, 0xffff0000, v221
	global_load_dwordx4 v[218:221], v[148:149], off offset:256
	v_lshl_add_u64 v[192:193], v[170:171], 1, v[144:145]
	v_pk_fma_f32 v[124:125], v[124:125], v[92:93], v[188:189]
	v_pk_fma_f32 v[126:127], v[126:127], v[94:95], v[190:191]
	v_pk_fma_f32 v[120:121], v[120:121], v[84:85], v[246:247]
	v_pk_fma_f32 v[122:123], v[122:123], v[86:87], v[248:249]
	v_cvt_pk_bf16_f32 v124, v124, v125
	v_cvt_pk_bf16_f32 v125, v126, v127
	v_cvt_pk_bf16_f32 v126, v120, v121
	v_cvt_pk_bf16_f32 v127, v122, v123
	global_store_dwordx4 v[192:193], v[124:127], off
	s_waitcnt vmcnt(11)
	v_lshlrev_b32_e32 v188, 16, v222
	v_and_b32_e32 v189, 0xffff0000, v222
	v_lshlrev_b32_e32 v190, 16, v223
	v_and_b32_e32 v191, 0xffff0000, v223
	v_lshlrev_b32_e32 v246, 16, v224
	v_and_b32_e32 v247, 0xffff0000, v224
	v_lshlrev_b32_e32 v248, 16, v225
	v_and_b32_e32 v249, 0xffff0000, v225
	v_lshl_add_u64 v[148:149], v[180:181], 1, v[144:145]
	global_load_dwordx4 v[222:225], v[148:149], off
	v_pk_fma_f32 v[116:117], v[116:117], v[76:77], v[188:189]
	v_pk_fma_f32 v[118:119], v[118:119], v[78:79], v[190:191]
	v_pk_fma_f32 v[112:113], v[112:113], v[72:73], v[246:247]
	v_pk_fma_f32 v[114:115], v[114:115], v[74:75], v[248:249]
	v_cvt_pk_bf16_f32 v116, v116, v117
	v_cvt_pk_bf16_f32 v117, v118, v119
	v_cvt_pk_bf16_f32 v118, v112, v113
	v_cvt_pk_bf16_f32 v119, v114, v115
	global_store_dwordx4 v[192:193], v[116:119], off offset:256
	s_waitcnt vmcnt(12)
	v_lshlrev_b32_e32 v188, 16, v226
	v_and_b32_e32 v189, 0xffff0000, v226
	v_lshlrev_b32_e32 v190, 16, v227
	v_and_b32_e32 v191, 0xffff0000, v227
	v_lshlrev_b32_e32 v246, 16, v228
	v_and_b32_e32 v247, 0xffff0000, v228
	v_lshlrev_b32_e32 v248, 16, v229
	v_and_b32_e32 v249, 0xffff0000, v229
	global_load_dwordx4 v[226:229], v[148:149], off offset:256
	v_lshl_add_u64 v[150:151], v[172:173], 1, v[144:145]
	v_pk_fma_f32 v[108:109], v[108:109], v[92:93], v[188:189]
	v_pk_fma_f32 v[110:111], v[110:111], v[94:95], v[190:191]
	v_pk_fma_f32 v[104:105], v[104:105], v[84:85], v[246:247]
	v_pk_fma_f32 v[106:107], v[106:107], v[86:87], v[248:249]
	v_cvt_pk_bf16_f32 v108, v108, v109
	v_cvt_pk_bf16_f32 v109, v110, v111
	v_cvt_pk_bf16_f32 v110, v104, v105
	v_cvt_pk_bf16_f32 v111, v106, v107
	global_store_dwordx4 v[150:151], v[108:111], off
	s_waitcnt vmcnt(13)
	v_lshlrev_b32_e32 v188, 16, v230
	v_and_b32_e32 v189, 0xffff0000, v230
	v_lshlrev_b32_e32 v190, 16, v231
	v_and_b32_e32 v191, 0xffff0000, v231
	v_lshlrev_b32_e32 v246, 16, v232
	v_and_b32_e32 v247, 0xffff0000, v232
	v_lshlrev_b32_e32 v248, 16, v233
	v_and_b32_e32 v249, 0xffff0000, v233
	v_lshl_add_u64 v[148:149], v[182:183], 1, v[144:145]
	global_load_dwordx4 v[230:233], v[148:149], off
	v_pk_fma_f32 v[100:101], v[100:101], v[76:77], v[188:189]
	v_pk_fma_f32 v[102:103], v[102:103], v[78:79], v[190:191]
	v_pk_fma_f32 v[96:97], v[96:97], v[72:73], v[246:247]
	v_pk_fma_f32 v[98:99], v[98:99], v[74:75], v[248:249]
	v_cvt_pk_bf16_f32 v100, v100, v101
	v_cvt_pk_bf16_f32 v101, v102, v103
	v_cvt_pk_bf16_f32 v102, v96, v97
	v_cvt_pk_bf16_f32 v103, v98, v99
	global_store_dwordx4 v[150:151], v[100:103], off offset:256
	s_waitcnt vmcnt(14)
	v_lshlrev_b32_e32 v188, 16, v234
	v_and_b32_e32 v189, 0xffff0000, v234
	v_lshlrev_b32_e32 v190, 16, v235
	v_and_b32_e32 v191, 0xffff0000, v235
	v_lshlrev_b32_e32 v246, 16, v236
	v_and_b32_e32 v247, 0xffff0000, v236
	v_lshlrev_b32_e32 v248, 16, v237
	v_and_b32_e32 v249, 0xffff0000, v237
	global_load_dwordx4 v[234:237], v[148:149], off offset:256
	v_lshl_add_u64 v[192:193], v[174:175], 1, v[144:145]
	v_pk_fma_f32 v[88:89], v[88:89], v[92:93], v[188:189]
	v_pk_fma_f32 v[90:91], v[90:91], v[94:95], v[190:191]
	v_pk_fma_f32 v[80:81], v[80:81], v[84:85], v[246:247]
	v_pk_fma_f32 v[82:83], v[82:83], v[86:87], v[248:249]
	v_cvt_pk_bf16_f32 v88, v88, v89
	v_cvt_pk_bf16_f32 v89, v90, v91
	v_cvt_pk_bf16_f32 v90, v80, v81
	v_cvt_pk_bf16_f32 v91, v82, v83
	global_store_dwordx4 v[192:193], v[88:91], off
	s_waitcnt vmcnt(15)
	v_lshlrev_b32_e32 v188, 16, v238
	v_and_b32_e32 v189, 0xffff0000, v238
	v_lshlrev_b32_e32 v190, 16, v239
	v_and_b32_e32 v191, 0xffff0000, v239
	v_lshlrev_b32_e32 v246, 16, v240
	v_and_b32_e32 v247, 0xffff0000, v240
	v_lshlrev_b32_e32 v248, 16, v241
	v_and_b32_e32 v249, 0xffff0000, v241
	v_pk_fma_f32 v[68:69], v[68:69], v[76:77], v[188:189]
	v_pk_fma_f32 v[70:71], v[70:71], v[78:79], v[190:191]
	v_pk_fma_f32 v[64:65], v[64:65], v[72:73], v[246:247]
	v_pk_fma_f32 v[66:67], v[66:67], v[74:75], v[248:249]
	v_cvt_pk_bf16_f32 v68, v68, v69
	v_cvt_pk_bf16_f32 v69, v70, v71
	v_cvt_pk_bf16_f32 v70, v64, v65
	v_cvt_pk_bf16_f32 v71, v66, v67
	global_store_dwordx4 v[192:193], v[68:71], off offset:256
	s_waitcnt vmcnt(15)
	v_lshlrev_b32_e32 v188, 16, v242
	v_and_b32_e32 v189, 0xffff0000, v242
	v_lshlrev_b32_e32 v190, 16, v243
	v_and_b32_e32 v191, 0xffff0000, v243
	v_lshlrev_b32_e32 v246, 16, v244
	v_and_b32_e32 v247, 0xffff0000, v244
	v_lshlrev_b32_e32 v248, 16, v245
	v_and_b32_e32 v249, 0xffff0000, v245
	v_lshl_add_u64 v[150:151], v[176:177], 1, v[144:145]
	v_pk_fma_f32 v[60:61], v[60:61], v[92:93], v[188:189]
	v_pk_fma_f32 v[62:63], v[62:63], v[94:95], v[190:191]
	v_pk_fma_f32 v[56:57], v[56:57], v[84:85], v[246:247]
	v_pk_fma_f32 v[58:59], v[58:59], v[86:87], v[248:249]
	v_cvt_pk_bf16_f32 v60, v60, v61
	v_cvt_pk_bf16_f32 v61, v62, v63
	v_cvt_pk_bf16_f32 v62, v56, v57
	v_cvt_pk_bf16_f32 v63, v58, v59
	global_store_dwordx4 v[150:151], v[60:63], off
	s_waitcnt vmcnt(15)
	v_lshlrev_b32_e32 v188, 16, v210
	v_and_b32_e32 v189, 0xffff0000, v210
	v_lshlrev_b32_e32 v190, 16, v211
	v_and_b32_e32 v191, 0xffff0000, v211
	v_lshlrev_b32_e32 v246, 16, v212
	v_and_b32_e32 v247, 0xffff0000, v212
	v_lshlrev_b32_e32 v248, 16, v213
	v_and_b32_e32 v249, 0xffff0000, v213
	v_pk_fma_f32 v[52:53], v[52:53], v[76:77], v[188:189]
	v_pk_fma_f32 v[54:55], v[54:55], v[78:79], v[190:191]
	v_pk_fma_f32 v[48:49], v[48:49], v[72:73], v[246:247]
	v_pk_fma_f32 v[50:51], v[50:51], v[74:75], v[248:249]
	v_cvt_pk_bf16_f32 v52, v52, v53
	v_cvt_pk_bf16_f32 v53, v54, v55
	v_cvt_pk_bf16_f32 v54, v48, v49
	v_cvt_pk_bf16_f32 v55, v50, v51
	global_store_dwordx4 v[150:151], v[52:55], off offset:256
	s_waitcnt vmcnt(14)
	v_lshlrev_b32_e32 v188, 16, v214
	v_and_b32_e32 v189, 0xffff0000, v214
	v_lshlrev_b32_e32 v190, 16, v215
	v_and_b32_e32 v191, 0xffff0000, v215
	v_lshlrev_b32_e32 v246, 16, v216
	v_and_b32_e32 v247, 0xffff0000, v216
	v_lshlrev_b32_e32 v248, 16, v217
	v_and_b32_e32 v249, 0xffff0000, v217
	v_lshl_add_u64 v[192:193], v[178:179], 1, v[144:145]
	v_pk_fma_f32 v[44:45], v[44:45], v[92:93], v[188:189]
	v_pk_fma_f32 v[46:47], v[46:47], v[94:95], v[190:191]
	v_pk_fma_f32 v[40:41], v[40:41], v[84:85], v[246:247]
	v_pk_fma_f32 v[42:43], v[42:43], v[86:87], v[248:249]
	v_cvt_pk_bf16_f32 v44, v44, v45
	v_cvt_pk_bf16_f32 v45, v46, v47
	v_cvt_pk_bf16_f32 v46, v40, v41
	v_cvt_pk_bf16_f32 v47, v42, v43
	global_store_dwordx4 v[192:193], v[44:47], off
	s_waitcnt vmcnt(13)
	v_lshlrev_b32_e32 v188, 16, v218
	v_and_b32_e32 v189, 0xffff0000, v218
	v_lshlrev_b32_e32 v190, 16, v219
	v_and_b32_e32 v191, 0xffff0000, v219
	v_lshlrev_b32_e32 v246, 16, v220
	v_and_b32_e32 v247, 0xffff0000, v220
	v_lshlrev_b32_e32 v248, 16, v221
	v_and_b32_e32 v249, 0xffff0000, v221
	v_pk_fma_f32 v[36:37], v[36:37], v[76:77], v[188:189]
	v_pk_fma_f32 v[38:39], v[38:39], v[78:79], v[190:191]
	v_pk_fma_f32 v[32:33], v[32:33], v[72:73], v[246:247]
	v_pk_fma_f32 v[34:35], v[34:35], v[74:75], v[248:249]
	v_cvt_pk_bf16_f32 v36, v36, v37
	v_cvt_pk_bf16_f32 v37, v38, v39
	v_cvt_pk_bf16_f32 v38, v32, v33
	v_cvt_pk_bf16_f32 v39, v34, v35
	global_store_dwordx4 v[192:193], v[36:39], off offset:256
	s_waitcnt vmcnt(12)
	v_lshlrev_b32_e32 v188, 16, v222
	v_and_b32_e32 v189, 0xffff0000, v222
	v_lshlrev_b32_e32 v190, 16, v223
	v_and_b32_e32 v191, 0xffff0000, v223
	v_lshlrev_b32_e32 v246, 16, v224
	v_and_b32_e32 v247, 0xffff0000, v224
	v_lshlrev_b32_e32 v248, 16, v225
	v_and_b32_e32 v249, 0xffff0000, v225
	v_lshl_add_u64 v[150:151], v[180:181], 1, v[144:145]
	v_pk_fma_f32 v[28:29], v[28:29], v[92:93], v[188:189]
	v_pk_fma_f32 v[30:31], v[30:31], v[94:95], v[190:191]
	v_pk_fma_f32 v[24:25], v[24:25], v[84:85], v[246:247]
	v_pk_fma_f32 v[26:27], v[26:27], v[86:87], v[248:249]
	v_cvt_pk_bf16_f32 v28, v28, v29
	v_cvt_pk_bf16_f32 v29, v30, v31
	v_cvt_pk_bf16_f32 v30, v24, v25
	v_cvt_pk_bf16_f32 v31, v26, v27
	global_store_dwordx4 v[150:151], v[28:31], off
	s_waitcnt vmcnt(11)
	v_lshlrev_b32_e32 v188, 16, v226
	v_and_b32_e32 v189, 0xffff0000, v226
	v_lshlrev_b32_e32 v190, 16, v227
	v_and_b32_e32 v191, 0xffff0000, v227
	v_lshlrev_b32_e32 v246, 16, v228
	v_and_b32_e32 v247, 0xffff0000, v228
	v_lshlrev_b32_e32 v248, 16, v229
	v_and_b32_e32 v249, 0xffff0000, v229
	v_pk_fma_f32 v[20:21], v[20:21], v[76:77], v[188:189]
	v_pk_fma_f32 v[22:23], v[22:23], v[78:79], v[190:191]
	v_pk_fma_f32 v[16:17], v[16:17], v[72:73], v[246:247]
	v_pk_fma_f32 v[18:19], v[18:19], v[74:75], v[248:249]
	v_cvt_pk_bf16_f32 v20, v20, v21
	v_cvt_pk_bf16_f32 v21, v22, v23
	v_cvt_pk_bf16_f32 v22, v16, v17
	v_cvt_pk_bf16_f32 v23, v18, v19
	global_store_dwordx4 v[150:151], v[20:23], off offset:256
	s_waitcnt vmcnt(10)
	v_lshlrev_b32_e32 v188, 16, v230
	v_and_b32_e32 v189, 0xffff0000, v230
	v_lshlrev_b32_e32 v190, 16, v231
	v_and_b32_e32 v191, 0xffff0000, v231
	v_lshlrev_b32_e32 v246, 16, v232
	v_and_b32_e32 v247, 0xffff0000, v232
	v_lshlrev_b32_e32 v248, 16, v233
	v_and_b32_e32 v249, 0xffff0000, v233
	v_lshl_add_u64 v[192:193], v[182:183], 1, v[144:145]
	v_pk_fma_f32 v[12:13], v[12:13], v[92:93], v[188:189]
	v_pk_fma_f32 v[14:15], v[14:15], v[94:95], v[190:191]
	v_pk_fma_f32 v[8:9], v[8:9], v[84:85], v[246:247]
	v_pk_fma_f32 v[10:11], v[10:11], v[86:87], v[248:249]
	v_cvt_pk_bf16_f32 v12, v12, v13
	v_cvt_pk_bf16_f32 v13, v14, v15
	v_cvt_pk_bf16_f32 v14, v8, v9
	v_cvt_pk_bf16_f32 v15, v10, v11
	global_store_dwordx4 v[192:193], v[12:15], off
	s_waitcnt vmcnt(9)
	v_lshlrev_b32_e32 v188, 16, v234
	v_and_b32_e32 v189, 0xffff0000, v234
	v_lshlrev_b32_e32 v190, 16, v235
	v_and_b32_e32 v191, 0xffff0000, v235
	v_lshlrev_b32_e32 v246, 16, v236
	v_and_b32_e32 v247, 0xffff0000, v236
	v_lshlrev_b32_e32 v248, 16, v237
	v_and_b32_e32 v249, 0xffff0000, v237
	v_pk_fma_f32 v[4:5], v[4:5], v[76:77], v[188:189]
	v_pk_fma_f32 v[6:7], v[6:7], v[78:79], v[190:191]
	v_pk_fma_f32 v[0:1], v[0:1], v[72:73], v[246:247]
	v_pk_fma_f32 v[2:3], v[2:3], v[74:75], v[248:249]
	v_cvt_pk_bf16_f32 v4, v4, v5
	v_cvt_pk_bf16_f32 v5, v6, v7
	v_cvt_pk_bf16_f32 v6, v0, v1
	v_cvt_pk_bf16_f32 v7, v2, v3
	global_store_dwordx4 v[192:193], v[4:7], off offset:256
	s_branch .Lwo_epi_done

.LBB0_773:
	s_add_u32 s22, s20, 0xfff80080
	s_addc_u32 s23, s21, -1
	s_add_i32 s61, 0, 0x10000
	v_add_u32_e32 v138, s61, v141
	ds_read_b128 v[144:147], v138
	ds_read_b128 v[148:151], v138 offset:1024
	ds_read_b128 v[162:165], v138 offset:2048
	ds_read_b128 v[166:169], v138 offset:3072
	s_cmp_eq_u32 s60, 28
	s_cselect_b32 s47, s35, s23
	s_cselect_b32 s46, s56, s22
	s_cselect_b32 s23, s25, s59
	s_cselect_b32 s22, s57, s58
	s_add_i32 m0, s5, 0xc000
	ds_read_b128 v[170:173], v143
	ds_read_b128 v[174:177], v143 offset:1024
	ds_read_b128 v[178:181], v143 offset:2048
	ds_read_b128 v[182:185], v143 offset:3072
	ds_read_b128 v[186:189], v143 offset:4096
	ds_read_b128 v[190:193], v143 offset:5120
	ds_read_b128 v[206:209], v143 offset:6144
	ds_read_b128 v[210:213], v143 offset:7168
	global_load_lds_dwordx4 v134, s[20:21]
	s_add_i32 m0, s5, 0xe000
	s_nop 0
	global_load_lds_dwordx4 v136, s[20:21]
	s_waitcnt lgkmcnt(8)
	s_barrier
	s_waitcnt lgkmcnt(0)
	s_setprio 1
	s_waitcnt lgkmcnt(0)
	v_mfma_f32_16x16x32_bf16 v[124:127], v[144:147], v[170:173], v[124:127]
	v_mfma_f32_16x16x32_bf16 v[120:123], v[162:165], v[170:173], v[120:123]
	v_mfma_f32_16x16x32_bf16 v[108:111], v[144:147], v[178:181], v[108:111]
	v_mfma_f32_16x16x32_bf16 v[104:107], v[162:165], v[178:181], v[104:107]
	v_mfma_f32_16x16x32_bf16 v[92:95], v[144:147], v[186:189], v[92:95]
	v_mfma_f32_16x16x32_bf16 v[88:91], v[162:165], v[186:189], v[88:91]
	v_mfma_f32_16x16x32_bf16 v[76:79], v[144:147], v[206:209], v[76:79]
	v_mfma_f32_16x16x32_bf16 v[72:75], v[162:165], v[206:209], v[72:75]
	v_mfma_f32_16x16x32_bf16 v[124:127], v[148:151], v[174:177], v[124:127]
	v_mfma_f32_16x16x32_bf16 v[120:123], v[166:169], v[174:177], v[120:123]
	v_mfma_f32_16x16x32_bf16 v[108:111], v[148:151], v[182:185], v[108:111]
	v_mfma_f32_16x16x32_bf16 v[104:107], v[166:169], v[182:185], v[104:107]
	v_mfma_f32_16x16x32_bf16 v[92:95], v[148:151], v[190:193], v[92:95]
	v_mfma_f32_16x16x32_bf16 v[88:91], v[166:169], v[190:193], v[88:91]
	v_mfma_f32_16x16x32_bf16 v[76:79], v[148:151], v[210:213], v[76:79]
	v_mfma_f32_16x16x32_bf16 v[72:75], v[166:169], v[210:213], v[72:75]
	s_setprio 0
	s_barrier
	s_add_i32 s68, 0, 0x14000
	v_add_u32_e32 v138, s68, v141
	s_add_i32 s61, s61, s4
	ds_read_b128 v[214:217], v138
	ds_read_b128 v[218:221], v138 offset:1024
	ds_read_b128 v[222:225], v138 offset:2048
	ds_read_b128 v[226:229], v138 offset:3072
	s_mov_b32 m0, s61
	s_nop 0
	global_load_lds_dwordx4 v152, s[22:23]
	s_add_i32 m0, s61, 0x2000
	s_nop 0
	global_load_lds_dwordx4 v132, s[22:23]
	s_barrier
	s_waitcnt lgkmcnt(0)
	s_setprio 1
	s_waitcnt lgkmcnt(0)
	v_mfma_f32_16x16x32_bf16 v[116:119], v[214:217], v[170:173], v[116:119]
	v_mfma_f32_16x16x32_bf16 v[112:115], v[222:225], v[170:173], v[112:115]
	v_mfma_f32_16x16x32_bf16 v[100:103], v[214:217], v[178:181], v[100:103]
	v_mfma_f32_16x16x32_bf16 v[96:99], v[222:225], v[178:181], v[96:99]
	v_mfma_f32_16x16x32_bf16 v[84:87], v[214:217], v[186:189], v[84:87]
	v_mfma_f32_16x16x32_bf16 v[80:83], v[222:225], v[186:189], v[80:83]
	v_mfma_f32_16x16x32_bf16 v[68:71], v[214:217], v[206:209], v[68:71]
	v_mfma_f32_16x16x32_bf16 v[64:67], v[222:225], v[206:209], v[64:67]
	v_mfma_f32_16x16x32_bf16 v[116:119], v[218:221], v[174:177], v[116:119]
	v_mfma_f32_16x16x32_bf16 v[112:115], v[226:229], v[174:177], v[112:115]
	v_mfma_f32_16x16x32_bf16 v[100:103], v[218:221], v[182:185], v[100:103]
	v_mfma_f32_16x16x32_bf16 v[96:99], v[226:229], v[182:185], v[96:99]
	v_mfma_f32_16x16x32_bf16 v[84:87], v[218:221], v[190:193], v[84:87]
	v_mfma_f32_16x16x32_bf16 v[80:83], v[226:229], v[190:193], v[80:83]
	v_mfma_f32_16x16x32_bf16 v[68:71], v[218:221], v[210:213], v[68:71]
	v_mfma_f32_16x16x32_bf16 v[64:67], v[226:229], v[210:213], v[64:67]
	s_setprio 0
	s_mov_b32 m0, s5
	s_add_u32 s98, s46, 0x80
	s_addc_u32 s99, s47, 0
	s_barrier
	ds_read_b128 v[170:173], v143 offset:16384
	ds_read_b128 v[174:177], v143 offset:17408
	ds_read_b128 v[178:181], v143 offset:18432
	ds_read_b128 v[182:185], v143 offset:19456
	ds_read_b128 v[186:189], v143 offset:20480
	ds_read_b128 v[190:193], v143 offset:21504
	ds_read_b128 v[206:209], v143 offset:22528
	ds_read_b128 v[210:213], v143 offset:23552
	global_load_lds_dwordx4 v128, s[46:47]
	s_mov_b32 m0, s50
	s_nop 0
	global_load_lds_dwordx4 v130, s[46:47]
	s_barrier
	s_waitcnt lgkmcnt(0)
	s_setprio 1
	s_waitcnt lgkmcnt(0)
	v_mfma_f32_16x16x32_bf16 v[60:63], v[144:147], v[170:173], v[60:63]
	v_mfma_f32_16x16x32_bf16 v[56:59], v[162:165], v[170:173], v[56:59]
	v_mfma_f32_16x16x32_bf16 v[44:47], v[144:147], v[178:181], v[44:47]
	v_mfma_f32_16x16x32_bf16 v[40:43], v[162:165], v[178:181], v[40:43]
	v_mfma_f32_16x16x32_bf16 v[28:31], v[144:147], v[186:189], v[28:31]
	v_mfma_f32_16x16x32_bf16 v[24:27], v[162:165], v[186:189], v[24:27]
	v_mfma_f32_16x16x32_bf16 v[12:15], v[144:147], v[206:209], v[12:15]
	v_mfma_f32_16x16x32_bf16 v[8:11], v[162:165], v[206:209], v[8:11]
	v_mfma_f32_16x16x32_bf16 v[60:63], v[148:151], v[174:177], v[60:63]
	v_mfma_f32_16x16x32_bf16 v[56:59], v[166:169], v[174:177], v[56:59]
	v_mfma_f32_16x16x32_bf16 v[44:47], v[148:151], v[182:185], v[44:47]
	v_mfma_f32_16x16x32_bf16 v[40:43], v[166:169], v[182:185], v[40:43]
	v_mfma_f32_16x16x32_bf16 v[28:31], v[148:151], v[190:193], v[28:31]
	v_mfma_f32_16x16x32_bf16 v[24:27], v[166:169], v[190:193], v[24:27]
	v_mfma_f32_16x16x32_bf16 v[12:15], v[148:151], v[210:213], v[12:15]
	v_mfma_f32_16x16x32_bf16 v[8:11], v[166:169], v[210:213], v[8:11]
	s_setprio 0
	s_barrier
	s_add_u32 s62, s22, 0x80000
	s_addc_u32 s63, s23, 0
	s_add_i32 s61, s68, s4
	s_mov_b32 m0, s61
	s_nop 0
	global_load_lds_dwordx4 v152, s[62:63]
	s_add_i32 m0, s61, 0x2000
	s_nop 0
	global_load_lds_dwordx4 v132, s[62:63]
	s_waitcnt vmcnt(6)
	s_barrier
	s_setprio 1
	v_mfma_f32_16x16x32_bf16 v[52:55], v[214:217], v[170:173], v[52:55]
	v_mfma_f32_16x16x32_bf16 v[48:51], v[222:225], v[170:173], v[48:51]
	v_mfma_f32_16x16x32_bf16 v[36:39], v[214:217], v[178:181], v[36:39]
	v_mfma_f32_16x16x32_bf16 v[32:35], v[222:225], v[178:181], v[32:35]
	v_mfma_f32_16x16x32_bf16 v[20:23], v[214:217], v[186:189], v[20:23]
	v_mfma_f32_16x16x32_bf16 v[16:19], v[222:225], v[186:189], v[16:19]
	v_mfma_f32_16x16x32_bf16 v[4:7], v[214:217], v[206:209], v[4:7]
	v_mfma_f32_16x16x32_bf16 v[0:3], v[222:225], v[206:209], v[0:3]
	v_mfma_f32_16x16x32_bf16 v[52:55], v[218:221], v[174:177], v[52:55]
	v_mfma_f32_16x16x32_bf16 v[48:51], v[226:229], v[174:177], v[48:51]
	v_mfma_f32_16x16x32_bf16 v[36:39], v[218:221], v[182:185], v[36:39]
	v_mfma_f32_16x16x32_bf16 v[32:35], v[226:229], v[182:185], v[32:35]
	v_mfma_f32_16x16x32_bf16 v[20:23], v[218:221], v[190:193], v[20:23]
	v_mfma_f32_16x16x32_bf16 v[16:19], v[226:229], v[190:193], v[16:19]
	v_mfma_f32_16x16x32_bf16 v[4:7], v[218:221], v[210:213], v[4:7]
	v_mfma_f32_16x16x32_bf16 v[0:3], v[226:229], v[210:213], v[0:3]
	s_setprio 0
	s_add_i32 s61, 0, 0x18000
	v_add_u32_e32 v166, s61, v141
	s_barrier
	ds_read_b128 v[144:147], v166
	ds_read_b128 v[148:151], v166 offset:1024
	ds_read_b128 v[162:165], v166 offset:2048
	ds_read_b128 v[166:169], v166 offset:3072
	s_add_u32 s46, s46, 0x80000
	s_addc_u32 s47, s47, 0
	s_mov_b32 m0, s51
	ds_read_b128 v[170:173], v143 offset:32768
	ds_read_b128 v[174:177], v143 offset:33792
	ds_read_b128 v[178:181], v143 offset:34816
	ds_read_b128 v[182:185], v143 offset:35840
	ds_read_b128 v[186:189], v143 offset:36864
	ds_read_b128 v[190:193], v143 offset:37888
	ds_read_b128 v[206:209], v143 offset:38912
	ds_read_b128 v[210:213], v143 offset:39936
	global_load_lds_dwordx4 v128, s[46:47]
	s_mov_b32 m0, s52
	s_nop 0
	global_load_lds_dwordx4 v130, s[46:47]
	s_waitcnt lgkmcnt(8)
	s_barrier
	s_waitcnt lgkmcnt(0)
	s_setprio 1
	s_waitcnt lgkmcnt(0)
	v_mfma_f32_16x16x32_bf16 v[124:127], v[144:147], v[170:173], v[124:127]
	v_mfma_f32_16x16x32_bf16 v[120:123], v[162:165], v[170:173], v[120:123]
	v_mfma_f32_16x16x32_bf16 v[108:111], v[144:147], v[178:181], v[108:111]
	v_mfma_f32_16x16x32_bf16 v[104:107], v[162:165], v[178:181], v[104:107]
	v_mfma_f32_16x16x32_bf16 v[92:95], v[144:147], v[186:189], v[92:95]
	v_mfma_f32_16x16x32_bf16 v[88:91], v[162:165], v[186:189], v[88:91]
	v_mfma_f32_16x16x32_bf16 v[76:79], v[144:147], v[206:209], v[76:79]
	v_mfma_f32_16x16x32_bf16 v[72:75], v[162:165], v[206:209], v[72:75]
	v_mfma_f32_16x16x32_bf16 v[124:127], v[148:151], v[174:177], v[124:127]
	v_mfma_f32_16x16x32_bf16 v[120:123], v[166:169], v[174:177], v[120:123]
	v_mfma_f32_16x16x32_bf16 v[108:111], v[148:151], v[182:185], v[108:111]
	v_mfma_f32_16x16x32_bf16 v[104:107], v[166:169], v[182:185], v[104:107]
	v_mfma_f32_16x16x32_bf16 v[92:95], v[148:151], v[190:193], v[92:95]
	v_mfma_f32_16x16x32_bf16 v[88:91], v[166:169], v[190:193], v[88:91]
	v_mfma_f32_16x16x32_bf16 v[76:79], v[148:151], v[210:213], v[76:79]
	v_mfma_f32_16x16x32_bf16 v[72:75], v[166:169], v[210:213], v[72:75]
	s_setprio 0
	s_barrier
	s_add_i32 s46, 0, 0x1c000
	s_add_i32 s47, s61, s4
	v_add_u32_e32 v205, s46, v141
	s_add_u32 s100, s22, 0x80
	s_addc_u32 s101, s23, 0
	s_mov_b32 m0, s47
	ds_read_b128 v[214:217], v205
	ds_read_b128 v[218:221], v205 offset:1024
	ds_read_b128 v[222:225], v205 offset:2048
	ds_read_b128 v[226:229], v205 offset:3072
	global_load_lds_dwordx4 v152, s[100:101]
	s_add_i32 m0, s47, 0x2000
	s_nop 0
	global_load_lds_dwordx4 v132, s[100:101]
	s_barrier
	s_waitcnt lgkmcnt(0)
	s_setprio 1
	s_waitcnt lgkmcnt(0)
	v_mfma_f32_16x16x32_bf16 v[116:119], v[214:217], v[170:173], v[116:119]
	v_mfma_f32_16x16x32_bf16 v[112:115], v[222:225], v[170:173], v[112:115]
	v_mfma_f32_16x16x32_bf16 v[100:103], v[214:217], v[178:181], v[100:103]
	v_mfma_f32_16x16x32_bf16 v[96:99], v[222:225], v[178:181], v[96:99]
	v_mfma_f32_16x16x32_bf16 v[84:87], v[214:217], v[186:189], v[84:87]
	v_mfma_f32_16x16x32_bf16 v[80:83], v[222:225], v[186:189], v[80:83]
	v_mfma_f32_16x16x32_bf16 v[68:71], v[214:217], v[206:209], v[68:71]
	v_mfma_f32_16x16x32_bf16 v[64:67], v[222:225], v[206:209], v[64:67]
	v_mfma_f32_16x16x32_bf16 v[116:119], v[218:221], v[174:177], v[116:119]
	v_mfma_f32_16x16x32_bf16 v[112:115], v[226:229], v[174:177], v[112:115]
	v_mfma_f32_16x16x32_bf16 v[100:103], v[218:221], v[182:185], v[100:103]
	v_mfma_f32_16x16x32_bf16 v[96:99], v[226:229], v[182:185], v[96:99]
	v_mfma_f32_16x16x32_bf16 v[84:87], v[218:221], v[190:193], v[84:87]
	v_mfma_f32_16x16x32_bf16 v[80:83], v[226:229], v[190:193], v[80:83]
	v_mfma_f32_16x16x32_bf16 v[68:71], v[218:221], v[210:213], v[68:71]
	v_mfma_f32_16x16x32_bf16 v[64:67], v[226:229], v[210:213], v[64:67]
	s_setprio 0
	s_mov_b32 m0, s53
	s_barrier
	ds_read_b128 v[170:173], v143 offset:49152
	ds_read_b128 v[174:177], v143 offset:50176
	ds_read_b128 v[178:181], v143 offset:51200
	ds_read_b128 v[182:185], v143 offset:52224
	ds_read_b128 v[186:189], v143 offset:53248
	ds_read_b128 v[190:193], v143 offset:54272
	ds_read_b128 v[206:209], v143 offset:55296
	ds_read_b128 v[210:213], v143 offset:56320
	global_load_lds_dwordx4 v128, s[98:99]
	s_mov_b32 m0, s54
	s_nop 0
	global_load_lds_dwordx4 v130, s[98:99]
	s_barrier
	s_waitcnt lgkmcnt(0)
	s_setprio 1
	s_waitcnt lgkmcnt(0)
	v_mfma_f32_16x16x32_bf16 v[60:63], v[144:147], v[170:173], v[60:63]
	v_mfma_f32_16x16x32_bf16 v[56:59], v[162:165], v[170:173], v[56:59]
	v_mfma_f32_16x16x32_bf16 v[44:47], v[144:147], v[178:181], v[44:47]
	v_mfma_f32_16x16x32_bf16 v[40:43], v[162:165], v[178:181], v[40:43]
	v_mfma_f32_16x16x32_bf16 v[28:31], v[144:147], v[186:189], v[28:31]
	v_mfma_f32_16x16x32_bf16 v[24:27], v[162:165], v[186:189], v[24:27]
	v_mfma_f32_16x16x32_bf16 v[12:15], v[144:147], v[206:209], v[12:15]
	v_mfma_f32_16x16x32_bf16 v[8:11], v[162:165], v[206:209], v[8:11]
	v_mfma_f32_16x16x32_bf16 v[60:63], v[148:151], v[174:177], v[60:63]
	v_mfma_f32_16x16x32_bf16 v[56:59], v[166:169], v[174:177], v[56:59]
	v_mfma_f32_16x16x32_bf16 v[44:47], v[148:151], v[182:185], v[44:47]
	v_mfma_f32_16x16x32_bf16 v[40:43], v[166:169], v[182:185], v[40:43]
	v_mfma_f32_16x16x32_bf16 v[28:31], v[148:151], v[190:193], v[28:31]
	v_mfma_f32_16x16x32_bf16 v[24:27], v[166:169], v[190:193], v[24:27]
	v_mfma_f32_16x16x32_bf16 v[12:15], v[148:151], v[210:213], v[12:15]
	v_mfma_f32_16x16x32_bf16 v[8:11], v[166:169], v[210:213], v[8:11]
	s_setprio 0
	s_barrier
	s_add_u32 s22, s22, 0x80080
	s_addc_u32 s23, s23, 0
	s_add_i32 s46, s46, s4
	s_mov_b32 m0, s46
	s_nop 0
	global_load_lds_dwordx4 v152, s[22:23]
	s_add_i32 m0, s46, 0x2000
	s_nop 0
	global_load_lds_dwordx4 v132, s[22:23]
	s_waitcnt vmcnt(6)
	s_barrier
	s_setprio 1
	v_mfma_f32_16x16x32_bf16 v[52:55], v[214:217], v[170:173], v[52:55]
	v_mfma_f32_16x16x32_bf16 v[48:51], v[222:225], v[170:173], v[48:51]
	v_mfma_f32_16x16x32_bf16 v[36:39], v[214:217], v[178:181], v[36:39]
	v_mfma_f32_16x16x32_bf16 v[32:35], v[222:225], v[178:181], v[32:35]
	v_mfma_f32_16x16x32_bf16 v[20:23], v[214:217], v[186:189], v[20:23]
	v_mfma_f32_16x16x32_bf16 v[16:19], v[222:225], v[186:189], v[16:19]
	v_mfma_f32_16x16x32_bf16 v[4:7], v[214:217], v[206:209], v[4:7]
	v_mfma_f32_16x16x32_bf16 v[0:3], v[222:225], v[206:209], v[0:3]
	v_mfma_f32_16x16x32_bf16 v[52:55], v[218:221], v[174:177], v[52:55]
	v_mfma_f32_16x16x32_bf16 v[48:51], v[226:229], v[174:177], v[48:51]
	v_mfma_f32_16x16x32_bf16 v[36:39], v[218:221], v[182:185], v[36:39]
	v_mfma_f32_16x16x32_bf16 v[32:35], v[226:229], v[182:185], v[32:35]
	v_mfma_f32_16x16x32_bf16 v[20:23], v[218:221], v[190:193], v[20:23]
	v_mfma_f32_16x16x32_bf16 v[16:19], v[226:229], v[190:193], v[16:19]
	v_mfma_f32_16x16x32_bf16 v[4:7], v[218:221], v[210:213], v[4:7]
	v_mfma_f32_16x16x32_bf16 v[0:3], v[226:229], v[210:213], v[0:3]
	s_setprio 0
	s_add_i32 s60, s60, 2
	s_add_u32 s20, s20, 0x100
	s_addc_u32 s21, s21, 0
	s_add_u32 s58, s58, 0x100
	s_addc_u32 s59, s59, 0
	s_cmp_gt_u32 s60, 29
	s_barrier
	s_cbranch_scc0 .LBB0_773
	v_lshl_add_u32 v144, s7, 8, v140
	v_max_f32_e32 v120, v120, v120
	v_ashrrev_i32_e32 v145, 31, v144
	v_max_f32_e32 v120, 0, v120
	v_max_f32_e32 v121, v121, v121
	v_max_f32_e32 v122, v122, v122
	v_lshl_or_b32 v138, s6, 8, v142
	v_lshlrev_b64 v[146:147], 14, v[144:145]
	v_mul_f32_e32 v145, v120, v120
	v_max_f32_e32 v120, v125, v125
	v_max_f32_e32 v121, 0, v121
	v_max_f32_e32 v122, 0, v122
	v_ashrrev_i32_e32 v139, 31, v138
	v_max_f32_e32 v124, v124, v124
	v_max_f32_e32 v120, 0, v120
	v_mul_f32_e32 v125, v121, v121
	v_max_f32_e32 v121, v126, v126
	v_mul_f32_e32 v126, v122, v122
	v_max_f32_e32 v122, v127, v127
	v_max_f32_e32 v123, v123, v123
	v_lshl_add_u64 v[146:147], s[16:17], 0, v[146:147]
	v_lshlrev_b64 v[148:149], 1, v[138:139]
	v_max_f32_e32 v124, 0, v124
	v_mul_f32_e32 v120, v120, v120
	v_max_f32_e32 v121, 0, v121
	v_max_f32_e32 v122, 0, v122
	v_max_f32_e32 v123, 0, v123
	v_max_f32_e32 v112, v112, v112
	v_lshl_add_u64 v[138:139], v[146:147], 0, v[148:149]
	v_mul_f32_e32 v124, v124, v124
	v_mul_f32_e32 v121, v121, v121
	v_mul_f32_e32 v122, v122, v122
	v_mul_f32_e32 v123, v123, v123
	v_cvt_pk_bf16_f32 v120, v124, v120
	v_max_f32_e32 v112, 0, v112
	v_max_f32_e32 v113, v113, v113
	v_max_f32_e32 v114, v114, v114
	v_cvt_pk_bf16_f32 v121, v121, v122
	v_cvt_pk_bf16_f32 v122, v145, v125
	v_cvt_pk_bf16_f32 v123, v126, v123
	global_store_dwordx4 v[138:139], v[120:123], off
	v_max_f32_e32 v113, 0, v113
	v_max_f32_e32 v114, 0, v114
	v_mul_f32_e32 v120, v112, v112
	v_max_f32_e32 v112, v117, v117
	v_max_f32_e32 v116, v116, v116
	v_max_f32_e32 v112, 0, v112
	v_mul_f32_e32 v117, v113, v113
	v_max_f32_e32 v113, v118, v118
	v_mul_f32_e32 v118, v114, v114
	v_max_f32_e32 v114, v119, v119
	v_max_f32_e32 v115, v115, v115
	v_max_f32_e32 v116, 0, v116
	v_mul_f32_e32 v112, v112, v112
	v_max_f32_e32 v113, 0, v113
	v_max_f32_e32 v114, 0, v114
	v_max_f32_e32 v115, 0, v115
	v_mul_f32_e32 v116, v116, v116
	v_mul_f32_e32 v113, v113, v113
	v_mul_f32_e32 v114, v114, v114
	v_mul_f32_e32 v115, v115, v115
	v_cvt_pk_bf16_f32 v112, v116, v112
	v_max_f32_e32 v104, v104, v104
	v_cvt_pk_bf16_f32 v113, v113, v114
	v_cvt_pk_bf16_f32 v114, v120, v117
	v_cvt_pk_bf16_f32 v115, v118, v115
	global_store_dwordx4 v[138:139], v[112:115], off offset:256
	v_max_f32_e32 v104, 0, v104
	v_max_f32_e32 v105, v105, v105
	v_or_b32_e32 v112, 16, v144
	v_max_f32_e32 v106, v106, v106
	v_ashrrev_i32_e32 v113, 31, v112
	v_mul_f32_e32 v114, v104, v104
	v_max_f32_e32 v104, v109, v109
	v_max_f32_e32 v105, 0, v105
	v_max_f32_e32 v106, 0, v106
	v_lshlrev_b64 v[112:113], 14, v[112:113]
	v_max_f32_e32 v108, v108, v108
	v_max_f32_e32 v104, 0, v104
	v_mul_f32_e32 v109, v105, v105
	v_max_f32_e32 v105, v110, v110
	v_mul_f32_e32 v110, v106, v106
	v_max_f32_e32 v106, v111, v111
	v_max_f32_e32 v107, v107, v107
	v_lshl_add_u64 v[112:113], s[16:17], 0, v[112:113]
	v_max_f32_e32 v108, 0, v108
	v_mul_f32_e32 v104, v104, v104
	v_max_f32_e32 v105, 0, v105
	v_max_f32_e32 v106, 0, v106
	v_max_f32_e32 v107, 0, v107
	v_max_f32_e32 v96, v96, v96
	v_lshl_add_u64 v[112:113], v[112:113], 0, v[148:149]
	v_mul_f32_e32 v108, v108, v108
	v_mul_f32_e32 v105, v105, v105
	v_mul_f32_e32 v106, v106, v106
	v_mul_f32_e32 v107, v107, v107
	v_cvt_pk_bf16_f32 v104, v108, v104
	v_max_f32_e32 v96, 0, v96
	v_max_f32_e32 v97, v97, v97
	v_max_f32_e32 v98, v98, v98
	v_cvt_pk_bf16_f32 v105, v105, v106
	v_cvt_pk_bf16_f32 v106, v114, v109
	v_cvt_pk_bf16_f32 v107, v110, v107
	global_store_dwordx4 v[112:113], v[104:107], off
	v_max_f32_e32 v97, 0, v97
	v_max_f32_e32 v98, 0, v98
	v_mul_f32_e32 v104, v96, v96
	v_max_f32_e32 v96, v101, v101
	v_max_f32_e32 v100, v100, v100
	v_max_f32_e32 v96, 0, v96
	v_mul_f32_e32 v101, v97, v97
	v_max_f32_e32 v97, v102, v102
	v_mul_f32_e32 v102, v98, v98
	v_max_f32_e32 v98, v103, v103
	v_max_f32_e32 v99, v99, v99
	v_max_f32_e32 v100, 0, v100
	v_mul_f32_e32 v96, v96, v96
	v_max_f32_e32 v97, 0, v97
	v_max_f32_e32 v98, 0, v98
	v_max_f32_e32 v99, 0, v99
	v_mul_f32_e32 v100, v100, v100
	v_mul_f32_e32 v97, v97, v97
	v_mul_f32_e32 v98, v98, v98
	v_mul_f32_e32 v99, v99, v99
	v_cvt_pk_bf16_f32 v96, v100, v96
	v_max_f32_e32 v88, v88, v88
	v_cvt_pk_bf16_f32 v97, v97, v98
	v_cvt_pk_bf16_f32 v98, v104, v101
	v_cvt_pk_bf16_f32 v99, v102, v99
	global_store_dwordx4 v[112:113], v[96:99], off offset:256
	v_max_f32_e32 v88, 0, v88
	v_max_f32_e32 v89, v89, v89
	v_or_b32_e32 v96, 32, v144
	v_max_f32_e32 v90, v90, v90
	v_ashrrev_i32_e32 v97, 31, v96
	v_mul_f32_e32 v98, v88, v88
	v_max_f32_e32 v88, v93, v93
	v_max_f32_e32 v89, 0, v89
	v_max_f32_e32 v90, 0, v90
	v_lshlrev_b64 v[96:97], 14, v[96:97]
	v_max_f32_e32 v92, v92, v92
	v_max_f32_e32 v88, 0, v88
	v_mul_f32_e32 v93, v89, v89
	v_max_f32_e32 v89, v94, v94
	v_mul_f32_e32 v94, v90, v90
	v_max_f32_e32 v90, v95, v95
	v_max_f32_e32 v91, v91, v91
	v_lshl_add_u64 v[96:97], s[16:17], 0, v[96:97]
	v_max_f32_e32 v92, 0, v92
	v_mul_f32_e32 v88, v88, v88
	v_max_f32_e32 v89, 0, v89
	v_max_f32_e32 v90, 0, v90
	v_max_f32_e32 v91, 0, v91
	v_max_f32_e32 v80, v80, v80
	v_lshl_add_u64 v[96:97], v[96:97], 0, v[148:149]
	v_mul_f32_e32 v92, v92, v92
	v_mul_f32_e32 v89, v89, v89
	v_mul_f32_e32 v90, v90, v90
	v_mul_f32_e32 v91, v91, v91
	v_cvt_pk_bf16_f32 v88, v92, v88
	v_max_f32_e32 v80, 0, v80
	v_max_f32_e32 v81, v81, v81
	v_max_f32_e32 v82, v82, v82
	v_cvt_pk_bf16_f32 v89, v89, v90
	v_cvt_pk_bf16_f32 v90, v98, v93
	v_cvt_pk_bf16_f32 v91, v94, v91
	global_store_dwordx4 v[96:97], v[88:91], off
	v_max_f32_e32 v81, 0, v81
	v_max_f32_e32 v82, 0, v82
	v_mul_f32_e32 v88, v80, v80
	v_max_f32_e32 v80, v85, v85
	v_max_f32_e32 v84, v84, v84
	v_max_f32_e32 v80, 0, v80
	v_mul_f32_e32 v85, v81, v81
	v_max_f32_e32 v81, v86, v86
	v_mul_f32_e32 v86, v82, v82
	v_max_f32_e32 v82, v87, v87
	v_max_f32_e32 v83, v83, v83
	v_max_f32_e32 v84, 0, v84
	v_mul_f32_e32 v80, v80, v80
	v_max_f32_e32 v81, 0, v81
	v_max_f32_e32 v82, 0, v82
	v_max_f32_e32 v83, 0, v83
	v_mul_f32_e32 v84, v84, v84
	v_mul_f32_e32 v81, v81, v81
	v_mul_f32_e32 v82, v82, v82
	v_mul_f32_e32 v83, v83, v83
	v_cvt_pk_bf16_f32 v80, v84, v80
	v_max_f32_e32 v72, v72, v72
	v_cvt_pk_bf16_f32 v81, v81, v82
	v_cvt_pk_bf16_f32 v82, v88, v85
	v_cvt_pk_bf16_f32 v83, v86, v83
	global_store_dwordx4 v[96:97], v[80:83], off offset:256
	v_max_f32_e32 v72, 0, v72
	v_max_f32_e32 v73, v73, v73
	v_or_b32_e32 v80, 48, v144
	v_max_f32_e32 v74, v74, v74
	v_ashrrev_i32_e32 v81, 31, v80
	v_mul_f32_e32 v82, v72, v72
	v_max_f32_e32 v72, v77, v77
	v_max_f32_e32 v73, 0, v73
	v_max_f32_e32 v74, 0, v74
	v_lshlrev_b64 v[80:81], 14, v[80:81]
	v_max_f32_e32 v76, v76, v76
	v_max_f32_e32 v72, 0, v72
	v_mul_f32_e32 v77, v73, v73
	v_max_f32_e32 v73, v78, v78
	v_mul_f32_e32 v78, v74, v74
	v_max_f32_e32 v74, v79, v79
	v_max_f32_e32 v75, v75, v75
	v_lshl_add_u64 v[80:81], s[16:17], 0, v[80:81]
	v_max_f32_e32 v76, 0, v76
	v_mul_f32_e32 v72, v72, v72
	v_max_f32_e32 v73, 0, v73
	v_max_f32_e32 v74, 0, v74
	v_max_f32_e32 v75, 0, v75
	v_max_f32_e32 v64, v64, v64
	v_max_f32_e32 v65, v65, v65
	v_max_f32_e32 v66, v66, v66
	v_lshl_add_u64 v[80:81], v[80:81], 0, v[148:149]
	v_mul_f32_e32 v76, v76, v76
	v_mul_f32_e32 v73, v73, v73
	v_mul_f32_e32 v74, v74, v74
	v_mul_f32_e32 v75, v75, v75
	v_cvt_pk_bf16_f32 v72, v76, v72
	v_max_f32_e32 v64, 0, v64
	v_max_f32_e32 v65, 0, v65
	v_max_f32_e32 v66, 0, v66
	v_cvt_pk_bf16_f32 v73, v73, v74
	v_cvt_pk_bf16_f32 v74, v82, v77
	v_cvt_pk_bf16_f32 v75, v78, v75
	global_store_dwordx4 v[80:81], v[72:75], off
	v_max_f32_e32 v68, v68, v68
	v_max_f32_e32 v67, v67, v67
	v_mul_f32_e32 v72, v64, v64
	v_max_f32_e32 v64, v69, v69
	v_mul_f32_e32 v69, v65, v65
	v_max_f32_e32 v65, v70, v70
	v_mul_f32_e32 v70, v66, v66
	v_max_f32_e32 v66, v71, v71
	v_max_f32_e32 v64, 0, v64
	v_max_f32_e32 v65, 0, v65
	v_max_f32_e32 v66, 0, v66
	v_max_f32_e32 v68, 0, v68
	v_mul_f32_e32 v64, v64, v64
	v_mul_f32_e32 v65, v65, v65
	v_max_f32_e32 v67, 0, v67
	v_mul_f32_e32 v66, v66, v66
	v_max_f32_e32 v56, v56, v56
	v_mul_f32_e32 v68, v68, v68
	v_mul_f32_e32 v67, v67, v67
	v_cvt_pk_bf16_f32 v64, v68, v64
	v_cvt_pk_bf16_f32 v65, v65, v66
	v_cvt_pk_bf16_f32 v66, v72, v69
	v_max_f32_e32 v56, 0, v56
	v_max_f32_e32 v57, v57, v57
	v_max_f32_e32 v58, v58, v58
	v_cvt_pk_bf16_f32 v67, v70, v67
	global_store_dwordx4 v[80:81], v[64:67], off offset:256
	v_max_f32_e32 v60, v60, v60
	v_max_f32_e32 v57, 0, v57
	v_mul_f32_e32 v66, v56, v56
	v_max_f32_e32 v56, v61, v61
	v_max_f32_e32 v58, 0, v58
	s_mov_b64 s[6:7], 0x200000
	v_max_f32_e32 v60, 0, v60
	v_max_f32_e32 v56, 0, v56
	v_mul_f32_e32 v61, v57, v57
	v_max_f32_e32 v57, v62, v62
	v_mul_f32_e32 v62, v58, v58
	v_max_f32_e32 v58, v63, v63
	v_lshl_add_u64 v[64:65], v[138:139], 0, s[6:7]
	v_mul_f32_e32 v60, v60, v60
	v_mul_f32_e32 v56, v56, v56
	v_max_f32_e32 v57, 0, v57
	v_max_f32_e32 v58, 0, v58
	v_max_f32_e32 v59, v59, v59
	s_mov_b32 s6, 0x200000
	v_mul_f32_e32 v57, v57, v57
	v_max_f32_e32 v59, 0, v59
	v_mul_f32_e32 v58, v58, v58
	v_cvt_pk_bf16_f32 v56, v60, v56
	v_add_co_u32_e32 v60, vcc, s6, v138
	v_max_f32_e32 v48, v48, v48
	v_max_f32_e32 v49, v49, v49
	v_max_f32_e32 v50, v50, v50
	v_mul_f32_e32 v59, v59, v59
	v_cvt_pk_bf16_f32 v57, v57, v58
	v_cvt_pk_bf16_f32 v58, v66, v61
	v_addc_co_u32_e32 v61, vcc, 0, v139, vcc
	v_max_f32_e32 v48, 0, v48
	v_max_f32_e32 v49, 0, v49
	v_max_f32_e32 v50, 0, v50
	v_cvt_pk_bf16_f32 v59, v62, v59
	global_store_dwordx4 v[60:61], v[56:59], off
	v_max_f32_e32 v52, v52, v52
	v_max_f32_e32 v51, v51, v51
	v_mul_f32_e32 v56, v48, v48
	v_max_f32_e32 v48, v53, v53
	v_mul_f32_e32 v53, v49, v49
	v_max_f32_e32 v49, v54, v54
	v_mul_f32_e32 v54, v50, v50
	v_max_f32_e32 v50, v55, v55
	v_max_f32_e32 v48, 0, v48
	v_max_f32_e32 v49, 0, v49
	v_max_f32_e32 v50, 0, v50
	v_max_f32_e32 v52, 0, v52
	v_mul_f32_e32 v48, v48, v48
	v_mul_f32_e32 v49, v49, v49
	v_max_f32_e32 v51, 0, v51
	v_mul_f32_e32 v50, v50, v50
	v_max_f32_e32 v40, v40, v40
	v_mul_f32_e32 v52, v52, v52
	v_mul_f32_e32 v51, v51, v51
	v_cvt_pk_bf16_f32 v48, v52, v48
	v_cvt_pk_bf16_f32 v49, v49, v50
	v_cvt_pk_bf16_f32 v50, v56, v53
	v_max_f32_e32 v40, 0, v40
	v_max_f32_e32 v41, v41, v41
	v_max_f32_e32 v42, v42, v42
	v_cvt_pk_bf16_f32 v51, v54, v51
	global_store_dwordx4 v[64:65], v[48:51], off offset:256
	v_max_f32_e32 v44, v44, v44
	v_max_f32_e32 v41, 0, v41
	v_mul_f32_e32 v50, v40, v40
	v_max_f32_e32 v40, v45, v45
	v_max_f32_e32 v42, 0, v42
	s_mov_b64 s[6:7], 0x240000
	v_max_f32_e32 v44, 0, v44
	v_max_f32_e32 v40, 0, v40
	v_mul_f32_e32 v45, v41, v41
	v_max_f32_e32 v41, v46, v46
	v_mul_f32_e32 v46, v42, v42
	v_max_f32_e32 v42, v47, v47
	v_lshl_add_u64 v[48:49], v[138:139], 0, s[6:7]
	v_mul_f32_e32 v44, v44, v44
	v_mul_f32_e32 v40, v40, v40
	v_max_f32_e32 v41, 0, v41
	v_max_f32_e32 v42, 0, v42
	v_max_f32_e32 v43, v43, v43
	s_mov_b32 s6, 0x240000
	v_mul_f32_e32 v41, v41, v41
	v_max_f32_e32 v43, 0, v43
	v_mul_f32_e32 v42, v42, v42
	v_cvt_pk_bf16_f32 v40, v44, v40
	v_add_co_u32_e32 v44, vcc, s6, v138
	v_max_f32_e32 v32, v32, v32
	v_max_f32_e32 v33, v33, v33
	v_max_f32_e32 v34, v34, v34
	v_mul_f32_e32 v43, v43, v43
	v_cvt_pk_bf16_f32 v41, v41, v42
	v_cvt_pk_bf16_f32 v42, v50, v45
	v_addc_co_u32_e32 v45, vcc, 0, v139, vcc
	v_max_f32_e32 v32, 0, v32
	v_max_f32_e32 v33, 0, v33
	v_max_f32_e32 v34, 0, v34
	v_cvt_pk_bf16_f32 v43, v46, v43
	global_store_dwordx4 v[44:45], v[40:43], off
	v_max_f32_e32 v36, v36, v36
	v_max_f32_e32 v35, v35, v35
	v_mul_f32_e32 v40, v32, v32
	v_max_f32_e32 v32, v37, v37
	v_mul_f32_e32 v37, v33, v33
	v_max_f32_e32 v33, v38, v38
	v_mul_f32_e32 v38, v34, v34
	v_max_f32_e32 v34, v39, v39
	v_max_f32_e32 v32, 0, v32
	v_max_f32_e32 v33, 0, v33
	v_max_f32_e32 v34, 0, v34
	v_max_f32_e32 v36, 0, v36
	v_mul_f32_e32 v32, v32, v32
	v_mul_f32_e32 v33, v33, v33
	v_max_f32_e32 v35, 0, v35
	v_mul_f32_e32 v34, v34, v34
	v_max_f32_e32 v24, v24, v24
	v_mul_f32_e32 v36, v36, v36
	v_mul_f32_e32 v35, v35, v35
	v_cvt_pk_bf16_f32 v32, v36, v32
	v_cvt_pk_bf16_f32 v33, v33, v34
	v_cvt_pk_bf16_f32 v34, v40, v37
	v_max_f32_e32 v24, 0, v24
	v_max_f32_e32 v25, v25, v25
	v_max_f32_e32 v26, v26, v26
	v_cvt_pk_bf16_f32 v35, v38, v35
	global_store_dwordx4 v[48:49], v[32:35], off offset:256
	v_max_f32_e32 v28, v28, v28
	v_max_f32_e32 v25, 0, v25
	v_mul_f32_e32 v34, v24, v24
	v_max_f32_e32 v24, v29, v29
	v_max_f32_e32 v26, 0, v26
	s_mov_b64 s[6:7], 0x280000
	v_max_f32_e32 v28, 0, v28
	v_max_f32_e32 v24, 0, v24
	v_mul_f32_e32 v29, v25, v25
	v_max_f32_e32 v25, v30, v30
	v_mul_f32_e32 v30, v26, v26
	v_max_f32_e32 v26, v31, v31
	v_lshl_add_u64 v[32:33], v[138:139], 0, s[6:7]
	v_mul_f32_e32 v28, v28, v28
	v_mul_f32_e32 v24, v24, v24
	v_max_f32_e32 v25, 0, v25
	v_max_f32_e32 v26, 0, v26
	v_max_f32_e32 v27, v27, v27
	s_mov_b32 s6, 0x280000
	v_mul_f32_e32 v25, v25, v25
	v_max_f32_e32 v27, 0, v27
	v_mul_f32_e32 v26, v26, v26
	v_cvt_pk_bf16_f32 v24, v28, v24
	v_add_co_u32_e32 v28, vcc, s6, v138
	v_max_f32_e32 v16, v16, v16
	v_max_f32_e32 v17, v17, v17
	v_max_f32_e32 v18, v18, v18
	v_mul_f32_e32 v27, v27, v27
	v_cvt_pk_bf16_f32 v25, v25, v26
	v_cvt_pk_bf16_f32 v26, v34, v29
	v_addc_co_u32_e32 v29, vcc, 0, v139, vcc
	v_max_f32_e32 v16, 0, v16
	v_max_f32_e32 v17, 0, v17
	v_max_f32_e32 v18, 0, v18
	v_cvt_pk_bf16_f32 v27, v30, v27
	global_store_dwordx4 v[28:29], v[24:27], off
	v_max_f32_e32 v20, v20, v20
	v_max_f32_e32 v19, v19, v19
	v_mul_f32_e32 v24, v16, v16
	v_max_f32_e32 v16, v21, v21
	v_mul_f32_e32 v21, v17, v17
	v_max_f32_e32 v17, v22, v22
	v_mul_f32_e32 v22, v18, v18
	v_max_f32_e32 v18, v23, v23
	v_max_f32_e32 v16, 0, v16
	v_max_f32_e32 v17, 0, v17
	v_max_f32_e32 v18, 0, v18
	v_max_f32_e32 v20, 0, v20
	v_mul_f32_e32 v16, v16, v16
	v_mul_f32_e32 v17, v17, v17
	v_max_f32_e32 v19, 0, v19
	v_mul_f32_e32 v18, v18, v18
	v_max_f32_e32 v8, v8, v8
	v_mul_f32_e32 v20, v20, v20
	v_mul_f32_e32 v19, v19, v19
	v_cvt_pk_bf16_f32 v16, v20, v16
	v_cvt_pk_bf16_f32 v17, v17, v18
	v_cvt_pk_bf16_f32 v18, v24, v21
	v_max_f32_e32 v8, 0, v8
	v_max_f32_e32 v9, v9, v9
	v_max_f32_e32 v10, v10, v10
	v_cvt_pk_bf16_f32 v19, v22, v19
	global_store_dwordx4 v[32:33], v[16:19], off offset:256
	v_max_f32_e32 v12, v12, v12
	v_max_f32_e32 v9, 0, v9
	v_mul_f32_e32 v18, v8, v8
	v_max_f32_e32 v8, v13, v13
	v_max_f32_e32 v10, 0, v10
	s_mov_b64 s[6:7], 0x2c0000
	v_max_f32_e32 v12, 0, v12
	v_max_f32_e32 v8, 0, v8
	v_mul_f32_e32 v13, v9, v9
	v_max_f32_e32 v9, v14, v14
	v_mul_f32_e32 v14, v10, v10
	v_max_f32_e32 v10, v15, v15
	v_lshl_add_u64 v[16:17], v[138:139], 0, s[6:7]
	v_mul_f32_e32 v12, v12, v12
	v_mul_f32_e32 v8, v8, v8
	v_max_f32_e32 v9, 0, v9
	v_max_f32_e32 v10, 0, v10
	v_max_f32_e32 v11, v11, v11
	s_mov_b32 s6, 0x2c0000
	v_mul_f32_e32 v9, v9, v9
	v_max_f32_e32 v11, 0, v11
	v_mul_f32_e32 v10, v10, v10
	v_cvt_pk_bf16_f32 v8, v12, v8
	v_add_co_u32_e32 v12, vcc, s6, v138
	v_max_f32_e32 v0, v0, v0
	v_max_f32_e32 v1, v1, v1
	v_max_f32_e32 v2, v2, v2
	v_mul_f32_e32 v11, v11, v11
	v_cvt_pk_bf16_f32 v9, v9, v10
	v_cvt_pk_bf16_f32 v10, v18, v13
	v_addc_co_u32_e32 v13, vcc, 0, v139, vcc
	v_max_f32_e32 v0, 0, v0
	v_max_f32_e32 v1, 0, v1
	v_max_f32_e32 v2, 0, v2
	v_cvt_pk_bf16_f32 v11, v14, v11
	global_store_dwordx4 v[12:13], v[8:11], off
	v_max_f32_e32 v3, v3, v3
	v_max_f32_e32 v4, v4, v4
	v_mul_f32_e32 v8, v0, v0
	v_max_f32_e32 v0, v5, v5
	v_mul_f32_e32 v5, v1, v1
	v_max_f32_e32 v1, v6, v6
	v_mul_f32_e32 v6, v2, v2
	v_max_f32_e32 v2, v7, v7
	v_max_f32_e32 v0, 0, v0
	v_max_f32_e32 v1, 0, v1
	v_max_f32_e32 v2, 0, v2
	v_max_f32_e32 v3, 0, v3
	v_max_f32_e32 v4, 0, v4
	v_mul_f32_e32 v0, v0, v0
	v_mul_f32_e32 v1, v1, v1
	v_mul_f32_e32 v2, v2, v2
	v_mul_f32_e32 v3, v3, v3
	s_and_b64 vcc, exec, s[38:39]
	s_mov_b32 s6, s24
	s_mov_b32 s7, s34
	s_mov_b64 s[22:23], s[44:45]
	s_mov_b64 s[20:21], s[42:43]
	v_mul_f32_e32 v4, v4, v4
	v_cvt_pk_bf16_f32 v0, v4, v0
	v_cvt_pk_bf16_f32 v1, v1, v2
	v_cvt_pk_bf16_f32 v2, v8, v5
	v_cvt_pk_bf16_f32 v3, v6, v3
	global_store_dwordx4 v[16:17], v[0:3], off offset:256
	s_cbranch_vccz .LBB0_770
	s_waitcnt vmcnt(0)
	v_readlane_b32 s34, v253, 45
	s_cmpk_gt_u32 s14, 0xff
	v_readlane_b32 s35, v253, 46
	s_cbranch_scc1 .LBB0_777
	s_barrier

.LBB0_836:
	s_add_u32 s22, s20, 0xffe00080
	s_addc_u32 s23, s21, -1
	s_add_i32 s78, 0, 0x10000
	v_add_u32_e32 v136, s78, v183
	ds_read_b128 v[120:123], v136
	ds_read_b128 v[124:127], v136 offset:1024
	ds_read_b128 v[132:135], v136 offset:2048
	ds_read_b128 v[136:139], v136 offset:3072
	s_cmpk_eq_i32 s69, 0x7c
	s_cselect_b32 s35, s6, s23
	s_cselect_b32 s34, s7, s22
	s_cselect_b32 s23, s1, s68
	s_cselect_b32 s22, s17, s63
	s_add_i32 m0, s52, 0xc000
	ds_read_b128 v[186:189], v185
	ds_read_b128 v[190:193], v185 offset:1024
	ds_read_b128 v[206:209], v185 offset:2048
	ds_read_b128 v[210:213], v185 offset:3072
	ds_read_b128 v[214:217], v185 offset:4096
	ds_read_b128 v[218:221], v185 offset:5120
	ds_read_b128 v[222:225], v185 offset:6144
	ds_read_b128 v[226:229], v185 offset:7168
	global_load_lds_dwordx4 v176, s[20:21]
	s_add_i32 m0, s52, 0xe000
	s_nop 0
	global_load_lds_dwordx4 v178, s[20:21]
	s_waitcnt lgkmcnt(8)
	s_barrier
	s_waitcnt lgkmcnt(0)
	s_setprio 1
	s_waitcnt lgkmcnt(0)
	v_mfma_f32_16x16x32_bf16 v[140:143], v[120:123], v[186:189], v[140:143]
	v_mfma_f32_16x16x32_bf16 v[128:131], v[132:135], v[186:189], v[128:131]
	v_mfma_f32_16x16x32_bf16 v[112:115], v[120:123], v[206:209], v[112:115]
	v_mfma_f32_16x16x32_bf16 v[104:107], v[132:135], v[206:209], v[104:107]
	v_mfma_f32_16x16x32_bf16 v[96:99], v[120:123], v[214:217], v[96:99]
	v_mfma_f32_16x16x32_bf16 v[88:91], v[132:135], v[214:217], v[88:91]
	v_mfma_f32_16x16x32_bf16 v[80:83], v[120:123], v[222:225], v[80:83]
	v_mfma_f32_16x16x32_bf16 v[72:75], v[132:135], v[222:225], v[72:75]
	v_mfma_f32_16x16x32_bf16 v[140:143], v[124:127], v[190:193], v[140:143]
	v_mfma_f32_16x16x32_bf16 v[128:131], v[136:139], v[190:193], v[128:131]
	v_mfma_f32_16x16x32_bf16 v[112:115], v[124:127], v[210:213], v[112:115]
	v_mfma_f32_16x16x32_bf16 v[104:107], v[136:139], v[210:213], v[104:107]
	v_mfma_f32_16x16x32_bf16 v[96:99], v[124:127], v[218:221], v[96:99]
	v_mfma_f32_16x16x32_bf16 v[88:91], v[136:139], v[218:221], v[88:91]
	v_mfma_f32_16x16x32_bf16 v[80:83], v[124:127], v[226:229], v[80:83]
	v_mfma_f32_16x16x32_bf16 v[72:75], v[136:139], v[226:229], v[72:75]
	s_setprio 0
	s_barrier
	s_add_i32 s80, 0, 0x14000
	v_add_u32_e32 v180, s80, v183
	s_add_i32 s78, s78, s51
	ds_read_b128 v[230:233], v180
	ds_read_b128 v[234:237], v180 offset:1024
	ds_read_b128 v[238:241], v180 offset:2048
	ds_read_b128 v[242:245], v180 offset:3072
	s_mov_b32 m0, s78
	s_nop 0
	global_load_lds_dwordx4 v152, s[22:23]
	s_add_i32 m0, s78, 0x2000
	s_nop 0
	global_load_lds_dwordx4 v144, s[22:23]
	s_barrier
	s_waitcnt lgkmcnt(0)
	s_setprio 1
	s_waitcnt lgkmcnt(0)
	v_mfma_f32_16x16x32_bf16 v[116:119], v[230:233], v[186:189], v[116:119]
	v_mfma_f32_16x16x32_bf16 v[108:111], v[238:241], v[186:189], v[108:111]
	v_mfma_f32_16x16x32_bf16 v[100:103], v[230:233], v[206:209], v[100:103]
	v_mfma_f32_16x16x32_bf16 v[92:95], v[238:241], v[206:209], v[92:95]
	v_mfma_f32_16x16x32_bf16 v[84:87], v[230:233], v[214:217], v[84:87]
	v_mfma_f32_16x16x32_bf16 v[76:79], v[238:241], v[214:217], v[76:79]
	v_mfma_f32_16x16x32_bf16 v[68:71], v[230:233], v[222:225], v[68:71]
	v_mfma_f32_16x16x32_bf16 v[64:67], v[238:241], v[222:225], v[64:67]
	v_mfma_f32_16x16x32_bf16 v[116:119], v[234:237], v[190:193], v[116:119]
	v_mfma_f32_16x16x32_bf16 v[108:111], v[242:245], v[190:193], v[108:111]
	v_mfma_f32_16x16x32_bf16 v[100:103], v[234:237], v[210:213], v[100:103]
	v_mfma_f32_16x16x32_bf16 v[92:95], v[242:245], v[210:213], v[92:95]
	v_mfma_f32_16x16x32_bf16 v[84:87], v[234:237], v[218:221], v[84:87]
	v_mfma_f32_16x16x32_bf16 v[76:79], v[242:245], v[218:221], v[76:79]
	v_mfma_f32_16x16x32_bf16 v[68:71], v[234:237], v[226:229], v[68:71]
	v_mfma_f32_16x16x32_bf16 v[64:67], v[242:245], v[226:229], v[64:67]
	s_setprio 0
	s_mov_b32 m0, s52
	v_lshl_add_u64 v[248:249], s[34:35], 0, v[148:149]
	s_barrier
	ds_read_b128 v[186:189], v185 offset:16384
	ds_read_b128 v[190:193], v185 offset:17408
	ds_read_b128 v[206:209], v185 offset:18432
	ds_read_b128 v[210:213], v185 offset:19456
	ds_read_b128 v[214:217], v185 offset:20480
	ds_read_b128 v[218:221], v185 offset:21504
	ds_read_b128 v[222:225], v185 offset:22528
	ds_read_b128 v[226:229], v185 offset:23552
	global_load_lds_dwordx4 v148, s[34:35]
	v_lshl_add_u64 v[250:251], s[34:35], 0, v[146:147]
	s_mov_b32 m0, s53
	s_nop 0
	global_load_lds_dwordx4 v146, s[34:35]
	s_barrier
	s_waitcnt lgkmcnt(0)
	s_setprio 1
	s_waitcnt lgkmcnt(0)
	v_mfma_f32_16x16x32_bf16 v[60:63], v[120:123], v[186:189], v[60:63]
	v_mfma_f32_16x16x32_bf16 v[56:59], v[132:135], v[186:189], v[56:59]
	v_mfma_f32_16x16x32_bf16 v[48:51], v[120:123], v[206:209], v[48:51]
	v_mfma_f32_16x16x32_bf16 v[40:43], v[132:135], v[206:209], v[40:43]
	v_mfma_f32_16x16x32_bf16 v[32:35], v[120:123], v[214:217], v[32:35]
	v_mfma_f32_16x16x32_bf16 v[24:27], v[132:135], v[214:217], v[24:27]
	v_mfma_f32_16x16x32_bf16 v[16:19], v[120:123], v[222:225], v[16:19]
	v_mfma_f32_16x16x32_bf16 v[8:11], v[132:135], v[222:225], v[8:11]
	v_mfma_f32_16x16x32_bf16 v[60:63], v[124:127], v[190:193], v[60:63]
	v_mfma_f32_16x16x32_bf16 v[56:59], v[136:139], v[190:193], v[56:59]
	v_mfma_f32_16x16x32_bf16 v[48:51], v[124:127], v[210:213], v[48:51]
	v_mfma_f32_16x16x32_bf16 v[40:43], v[136:139], v[210:213], v[40:43]
	v_mfma_f32_16x16x32_bf16 v[32:35], v[124:127], v[218:221], v[32:35]
	v_mfma_f32_16x16x32_bf16 v[24:27], v[136:139], v[218:221], v[24:27]
	v_mfma_f32_16x16x32_bf16 v[16:19], v[124:127], v[226:229], v[16:19]
	v_mfma_f32_16x16x32_bf16 v[8:11], v[136:139], v[226:229], v[8:11]
	s_setprio 0
	s_barrier
	s_add_u32 s78, s22, 0x200000
	s_addc_u32 s79, s23, 0
	s_add_i32 s80, s80, s51
	s_mov_b32 m0, s80
	s_nop 0
	global_load_lds_dwordx4 v152, s[78:79]
	s_add_i32 m0, s80, 0x2000
	s_nop 0
	global_load_lds_dwordx4 v144, s[78:79]
	s_waitcnt vmcnt(6)
	s_barrier
	s_setprio 1
	v_mfma_f32_16x16x32_bf16 v[52:55], v[230:233], v[186:189], v[52:55]
	v_mfma_f32_16x16x32_bf16 v[44:47], v[238:241], v[186:189], v[44:47]
	v_mfma_f32_16x16x32_bf16 v[36:39], v[230:233], v[206:209], v[36:39]
	v_mfma_f32_16x16x32_bf16 v[28:31], v[238:241], v[206:209], v[28:31]
	v_mfma_f32_16x16x32_bf16 v[20:23], v[230:233], v[214:217], v[20:23]
	v_mfma_f32_16x16x32_bf16 v[12:15], v[238:241], v[214:217], v[12:15]
	v_mfma_f32_16x16x32_bf16 v[4:7], v[230:233], v[222:225], v[4:7]
	v_mfma_f32_16x16x32_bf16 v[0:3], v[238:241], v[222:225], v[0:3]
	v_mfma_f32_16x16x32_bf16 v[52:55], v[234:237], v[190:193], v[52:55]
	v_mfma_f32_16x16x32_bf16 v[44:47], v[242:245], v[190:193], v[44:47]
	v_mfma_f32_16x16x32_bf16 v[36:39], v[234:237], v[210:213], v[36:39]
	v_mfma_f32_16x16x32_bf16 v[28:31], v[242:245], v[210:213], v[28:31]
	v_mfma_f32_16x16x32_bf16 v[20:23], v[234:237], v[218:221], v[20:23]
	v_mfma_f32_16x16x32_bf16 v[12:15], v[242:245], v[218:221], v[12:15]
	v_mfma_f32_16x16x32_bf16 v[4:7], v[234:237], v[226:229], v[4:7]
	v_mfma_f32_16x16x32_bf16 v[0:3], v[242:245], v[226:229], v[0:3]
	s_setprio 0
	s_add_i32 s78, 0, 0x18000
	v_add_u32_e32 v136, s78, v183
	s_barrier
	ds_read_b128 v[120:123], v136
	ds_read_b128 v[124:127], v136 offset:1024
	ds_read_b128 v[132:135], v136 offset:2048
	ds_read_b128 v[136:139], v136 offset:3072
	s_add_u32 s34, s34, 0x200000
	s_addc_u32 s35, s35, 0
	s_mov_b32 m0, s54
	ds_read_b128 v[186:189], v185 offset:32768
	ds_read_b128 v[190:193], v185 offset:33792
	ds_read_b128 v[206:209], v185 offset:34816
	ds_read_b128 v[210:213], v185 offset:35840
	ds_read_b128 v[214:217], v185 offset:36864
	ds_read_b128 v[218:221], v185 offset:37888
	ds_read_b128 v[222:225], v185 offset:38912
	ds_read_b128 v[226:229], v185 offset:39936
	global_load_lds_dwordx4 v148, s[34:35]
	s_mov_b32 m0, s55
	s_nop 0
	global_load_lds_dwordx4 v146, s[34:35]
	s_waitcnt lgkmcnt(8)
	s_barrier
	s_waitcnt lgkmcnt(0)
	s_setprio 1
	s_waitcnt lgkmcnt(0)
	v_mfma_f32_16x16x32_bf16 v[140:143], v[120:123], v[186:189], v[140:143]
	v_mfma_f32_16x16x32_bf16 v[128:131], v[132:135], v[186:189], v[128:131]
	v_mfma_f32_16x16x32_bf16 v[112:115], v[120:123], v[206:209], v[112:115]
	v_mfma_f32_16x16x32_bf16 v[104:107], v[132:135], v[206:209], v[104:107]
	v_mfma_f32_16x16x32_bf16 v[96:99], v[120:123], v[214:217], v[96:99]
	v_mfma_f32_16x16x32_bf16 v[88:91], v[132:135], v[214:217], v[88:91]
	v_mfma_f32_16x16x32_bf16 v[80:83], v[120:123], v[222:225], v[80:83]
	v_mfma_f32_16x16x32_bf16 v[72:75], v[132:135], v[222:225], v[72:75]
	v_mfma_f32_16x16x32_bf16 v[140:143], v[124:127], v[190:193], v[140:143]
	v_mfma_f32_16x16x32_bf16 v[128:131], v[136:139], v[190:193], v[128:131]
	v_mfma_f32_16x16x32_bf16 v[112:115], v[124:127], v[210:213], v[112:115]
	v_mfma_f32_16x16x32_bf16 v[104:107], v[136:139], v[210:213], v[104:107]
	v_mfma_f32_16x16x32_bf16 v[96:99], v[124:127], v[218:221], v[96:99]
	v_mfma_f32_16x16x32_bf16 v[88:91], v[136:139], v[218:221], v[88:91]
	v_mfma_f32_16x16x32_bf16 v[80:83], v[124:127], v[226:229], v[80:83]
	v_mfma_f32_16x16x32_bf16 v[72:75], v[136:139], v[226:229], v[72:75]
	s_setprio 0
	s_barrier
	s_add_i32 s34, 0, 0x1c000
	s_add_i32 s35, s78, s51
	v_add_u32_e32 v205, s34, v183
	s_add_u32 s100, s22, 0x80
	s_addc_u32 s101, s23, 0
	s_mov_b32 m0, s35
	ds_read_b128 v[230:233], v205
	ds_read_b128 v[234:237], v205 offset:1024
	ds_read_b128 v[238:241], v205 offset:2048
	ds_read_b128 v[242:245], v205 offset:3072
	global_load_lds_dwordx4 v152, s[100:101]
	s_add_i32 m0, s35, 0x2000
	s_nop 0
	global_load_lds_dwordx4 v144, s[100:101]
	s_barrier
	s_waitcnt lgkmcnt(0)
	s_setprio 1
	s_waitcnt lgkmcnt(0)
	v_mfma_f32_16x16x32_bf16 v[116:119], v[230:233], v[186:189], v[116:119]
	v_mfma_f32_16x16x32_bf16 v[108:111], v[238:241], v[186:189], v[108:111]
	v_mfma_f32_16x16x32_bf16 v[100:103], v[230:233], v[206:209], v[100:103]
	v_mfma_f32_16x16x32_bf16 v[92:95], v[238:241], v[206:209], v[92:95]
	v_mfma_f32_16x16x32_bf16 v[84:87], v[230:233], v[214:217], v[84:87]
	v_mfma_f32_16x16x32_bf16 v[76:79], v[238:241], v[214:217], v[76:79]
	v_mfma_f32_16x16x32_bf16 v[68:71], v[230:233], v[222:225], v[68:71]
	v_mfma_f32_16x16x32_bf16 v[64:67], v[238:241], v[222:225], v[64:67]
	v_mfma_f32_16x16x32_bf16 v[116:119], v[234:237], v[190:193], v[116:119]
	v_mfma_f32_16x16x32_bf16 v[108:111], v[242:245], v[190:193], v[108:111]
	v_mfma_f32_16x16x32_bf16 v[100:103], v[234:237], v[210:213], v[100:103]
	v_mfma_f32_16x16x32_bf16 v[92:95], v[242:245], v[210:213], v[92:95]
	v_mfma_f32_16x16x32_bf16 v[84:87], v[234:237], v[218:221], v[84:87]
	v_mfma_f32_16x16x32_bf16 v[76:79], v[242:245], v[218:221], v[76:79]
	v_mfma_f32_16x16x32_bf16 v[68:71], v[234:237], v[226:229], v[68:71]
	v_mfma_f32_16x16x32_bf16 v[64:67], v[242:245], v[226:229], v[64:67]
	s_setprio 0
	s_mov_b32 m0, s60
	v_lshl_add_u64 v[180:181], v[248:249], 0, s[18:19]
	s_barrier
	ds_read_b128 v[186:189], v185 offset:49152
	ds_read_b128 v[190:193], v185 offset:50176
	ds_read_b128 v[206:209], v185 offset:51200
	ds_read_b128 v[210:213], v185 offset:52224
	ds_read_b128 v[214:217], v185 offset:53248
	ds_read_b128 v[218:221], v185 offset:54272
	ds_read_b128 v[222:225], v185 offset:55296
	ds_read_b128 v[226:229], v185 offset:56320
	global_load_lds_dwordx4 v[180:181], off
	v_lshl_add_u64 v[180:181], v[250:251], 0, s[18:19]
	s_mov_b32 m0, s61
	s_nop 0
	global_load_lds_dwordx4 v[180:181], off
	s_barrier
	s_waitcnt lgkmcnt(0)
	s_setprio 1
	s_waitcnt lgkmcnt(0)
	v_mfma_f32_16x16x32_bf16 v[60:63], v[120:123], v[186:189], v[60:63]
	v_mfma_f32_16x16x32_bf16 v[56:59], v[132:135], v[186:189], v[56:59]
	v_mfma_f32_16x16x32_bf16 v[48:51], v[120:123], v[206:209], v[48:51]
	v_mfma_f32_16x16x32_bf16 v[40:43], v[132:135], v[206:209], v[40:43]
	v_mfma_f32_16x16x32_bf16 v[32:35], v[120:123], v[214:217], v[32:35]
	v_mfma_f32_16x16x32_bf16 v[24:27], v[132:135], v[214:217], v[24:27]
	v_mfma_f32_16x16x32_bf16 v[16:19], v[120:123], v[222:225], v[16:19]
	v_mfma_f32_16x16x32_bf16 v[8:11], v[132:135], v[222:225], v[8:11]
	v_mfma_f32_16x16x32_bf16 v[60:63], v[124:127], v[190:193], v[60:63]
	v_mfma_f32_16x16x32_bf16 v[56:59], v[136:139], v[190:193], v[56:59]
	v_mfma_f32_16x16x32_bf16 v[48:51], v[124:127], v[210:213], v[48:51]
	v_mfma_f32_16x16x32_bf16 v[40:43], v[136:139], v[210:213], v[40:43]
	v_mfma_f32_16x16x32_bf16 v[32:35], v[124:127], v[218:221], v[32:35]
	v_mfma_f32_16x16x32_bf16 v[24:27], v[136:139], v[218:221], v[24:27]
	v_mfma_f32_16x16x32_bf16 v[16:19], v[124:127], v[226:229], v[16:19]
	v_mfma_f32_16x16x32_bf16 v[8:11], v[136:139], v[226:229], v[8:11]
	s_setprio 0
	s_barrier
	s_add_u32 s22, s22, 0x200080
	s_addc_u32 s23, s23, 0
	s_add_i32 s34, s34, s51
	s_mov_b32 m0, s34
	s_nop 0
	global_load_lds_dwordx4 v152, s[22:23]
	s_add_i32 m0, s34, 0x2000
	s_nop 0
	global_load_lds_dwordx4 v144, s[22:23]
	s_waitcnt vmcnt(6)
	s_barrier
	s_setprio 1
	v_mfma_f32_16x16x32_bf16 v[52:55], v[230:233], v[186:189], v[52:55]
	v_mfma_f32_16x16x32_bf16 v[44:47], v[238:241], v[186:189], v[44:47]
	v_mfma_f32_16x16x32_bf16 v[36:39], v[230:233], v[206:209], v[36:39]
	v_mfma_f32_16x16x32_bf16 v[28:31], v[238:241], v[206:209], v[28:31]
	v_mfma_f32_16x16x32_bf16 v[20:23], v[230:233], v[214:217], v[20:23]
	v_mfma_f32_16x16x32_bf16 v[12:15], v[238:241], v[214:217], v[12:15]
	v_mfma_f32_16x16x32_bf16 v[4:7], v[230:233], v[222:225], v[4:7]
	v_mfma_f32_16x16x32_bf16 v[0:3], v[238:241], v[222:225], v[0:3]
	v_mfma_f32_16x16x32_bf16 v[52:55], v[234:237], v[190:193], v[52:55]
	v_mfma_f32_16x16x32_bf16 v[44:47], v[242:245], v[190:193], v[44:47]
	v_mfma_f32_16x16x32_bf16 v[36:39], v[234:237], v[210:213], v[36:39]
	v_mfma_f32_16x16x32_bf16 v[28:31], v[242:245], v[210:213], v[28:31]
	v_mfma_f32_16x16x32_bf16 v[20:23], v[234:237], v[218:221], v[20:23]
	v_mfma_f32_16x16x32_bf16 v[12:15], v[242:245], v[218:221], v[12:15]
	v_mfma_f32_16x16x32_bf16 v[4:7], v[234:237], v[226:229], v[4:7]
	v_mfma_f32_16x16x32_bf16 v[0:3], v[242:245], v[226:229], v[0:3]
	s_setprio 0
	s_add_i32 s69, s69, 2
	s_add_u32 s20, s20, 0x100
	s_addc_u32 s21, s21, 0
	s_add_u32 s63, s63, 0x100
	s_addc_u32 s68, s68, 0
	s_cmpk_gt_u32 s69, 0x7d
	s_barrier
	s_cbranch_scc0 .LBB0_836
	s_cmp_eq_u32 s99, 0
	s_cbranch_scc1 .Lm2_epi
	s_and_b32 s100, s2, 0x7f
	s_lshl_b32 s100, s100, 18
	s_add_u32 s100, s100, 0x29800000
	s_add_u32 s100, s46, s100
	s_addc_u32 s101, s47, 0
	v_lshlrev_b32_e32 v186, 4, v182
	s_cmp_eq_u32 s99, 1
	s_cbranch_scc1 .Lm2_put_partial
	s_and_b32 s6, s2, 0x7f
	s_lshl_b32 s6, s6, 6
	s_add_u32 s6, s6, 0x2970a000
	s_add_u32 s6, s46, s6
	s_addc_u32 s7, s47, 0
	v_mov_b32_e32 v187, 0
	s_mov_b32 s99, 0
